# MFMA-to-VALU hazard pads s_nop 15 x2 trimmed to s_nop 11 (10 sites); rope/retention table generation on workgroups with a single modulation task
# baseline (speedup 1.0000x reference)
; template <bool OVL, bool PANEL = false, class Epi>
; __device__ __forceinline__ void gemm_phase(const bf16_t* __restrict__ A, long lda, const bf16_t* __restrict__ Bt, long ldb, int nM, int nN, int K,
;                                            const Epi& epi, bf16_t* shm, int w0) {
;     ...
;     asm volatile("s_nop 15\n\ts_nop 15" ::: "memory");
;   __device__ __forceinline__ void operator()(f32x4 (&acc)[2][2][4][2], int pm, int pn, int wr_, int wc_, int fr_, int fq_, bf16_t* shm, int tid) const {
;     ...
;     const float* Xr = (!fdown && l == 0) ? (pm < 256 ? p.x : p.ctx - (long)NLAT * DM) : (const float*)X;
;     const long bio = (long)row_bi(pm * 256) * 6144;
;     f2_t* red = (f2_t*)((char*)shm + 128 * 1024);
;     f2_t* rst = (f2_t*)((char*)shm + 128 * 1024 + 8192);
;     float s1[8], s2[8];
; #pragma unroll
;     for (int i = 0; i < 8; ++i) { s1[i] = 0.f; s2[i] = 0.f; }
; #pragma unroll
;     for (int bj = 0; bj < 2; ++bj)
; #pragma unroll
;       for (int n = 0; n < 2; ++n) {
;         asm volatile("" ::: "memory");
;         const int col = pn * 256 + bj * 128 + wc * 32 + n * 16 + fq * 4;
;         f32x4 lg = {1.f, 1.f, 1.f, 1.f}, lb = {0.f, 0.f, 0.f, 0.f};
;         if (stats) { lg = *(const f32x4*)(lng + col); lb = *(const f32x4*)(lnb + col); }
;         const f32x4 gv = *(const f32x4*)(g + bio + col);
; #pragma unroll
;         for (int ai = 0; ai < 2; ++ai)
; #pragma unroll
;           for (int m = 0; m < 4; ++m) {
;             const int row = pm * 256 + ai * 128 + wr * 64 + m * 16 + fr;
;             const f32x4 v = acc[ai][bj][m][n];
;             f32x4* xp = (f32x4*)(X + (long)row * DM + col);
;             f32x4 xv = *(const f32x4*)(Xr + (long)row * DM + col);
;             if (stats) { const float mu = stats[2 * row], rs = stats[2 * row + 1]; xv = (xv - mu) * rs * lg + lb; }
;             xv = xv * ALPHA + gv * v; *xp = xv;
.LBB0_130:
	v_readlane_b32 s1, v250, 0
	s_nop 11
	v_mbcnt_lo_u32_b32 v138, -1, 0
	v_mbcnt_hi_u32_b32 v138, -1, v138
	s_lshl_b32 s0, s29, 8
	v_bfe_u32 v216, v138, 4, 2
	v_add_u32_e32 v148, s1, v138
	v_bfe_u32 v215, v148, 6, 2
	v_lshlrev_b32_e32 v0, 5, v215
	v_lshlrev_b32_e32 v130, 2, v216
	v_or3_b32 v0, v0, v130, s0
	v_readlane_b32 s0, v250, 51
	v_readlane_b32 s1, v250, 52
	v_lshlrev_b64 v[146:147], 2, v[0:1]
	s_andn2_b64 vcc, exec, s[0:1]
	v_cndmask_b32_e64 v130, 0, 1, s[0:1]
	v_cmp_ne_u32_e64 s[8:9], 1, v130
	v_lshl_add_u64 v[162:163], s[84:85], 0, v[146:147]
	v_lshl_add_u64 v[164:165], s[86:87], 0, v[146:147]
	s_min_i32 s0, s28, 0x10000
	s_ashr_i32 s0, s0, 11
	s_mul_hi_i32 s1, s0, 0x1800
	s_mulk_i32 s0, 0x1800
	s_lshl_b64 s[0:1], s[0:1], 2
	v_and_b32_e32 v149, 15, v138
	v_ashrrev_i32_e32 v138, 2, v148
	v_and_b32_e32 v214, 0xffffffc0, v138
	v_or_b32_e32 v138, s28, v149
	v_add_u32_e32 v227, v214, v138
	s_add_u32 s50, s78, s0
	s_addc_u32 s51, s79, s1
	v_readlane_b32 s52, v252, 24
	v_readlane_b32 s53, v252, 25
	v_readlane_b32 s44, v253, 21
	v_readlane_b32 s45, v253, 22
	s_mov_b64 s[54:55], s[52:53]
	s_and_b64 vcc, exec, s[8:9]
	s_cselect_b32 s44, s54, s44
	s_cselect_b32 s45, s55, s45
	s_cselect_b32 s46, s50, s84
	s_cselect_b32 s47, s51, s85
	s_cselect_b32 s48, s50, s86
	s_cselect_b32 s49, s51, s87
	v_lshlrev_b32_e32 v225, 3, v227
	v_lshlrev_b32_e32 v217, 12, v227
	v_add_u32_e32 v217, v217, v146
	v_add_u32_e32 v218, 0x10000, v217
	v_add_u32_e32 v219, 0x20000, v217
	v_add_u32_e32 v220, 0x30000, v217
	v_add_u32_e32 v221, 0x80000, v217
	v_add_u32_e32 v222, 0x90000, v217
	v_add_u32_e32 v223, 0xa0000, v217
	v_add_u32_e32 v224, 0xb0000, v217
	global_load_dwordx2 v[130:131], v225, s[44:45]
	global_load_dwordx2 v[132:133], v225, s[44:45] offset:128
	global_load_dwordx2 v[134:135], v225, s[44:45] offset:256
	global_load_dwordx2 v[136:137], v225, s[44:45] offset:384
	global_load_dwordx2 v[138:139], v225, s[44:45] offset:1024
	global_load_dwordx2 v[140:141], v225, s[44:45] offset:1152
	global_load_dwordx2 v[142:143], v225, s[44:45] offset:1280
	global_load_dwordx2 v[144:145], v225, s[44:45] offset:1408
	global_load_dwordx4 v[228:231], v146, s[46:47]
	global_load_dwordx4 v[232:235], v146, s[48:49]
	global_load_dwordx4 v[236:239], v146, s[50:51]
	global_load_dwordx4 v[150:153], v217, s[52:53]
	global_load_dwordx4 v[154:157], v218, s[52:53]
	global_load_dwordx4 v[158:161], v219, s[52:53]
	global_load_dwordx4 v[162:165], v220, s[52:53]
	global_load_dwordx4 v[166:169], v221, s[52:53]
	global_load_dwordx4 v[170:173], v222, s[52:53]
	global_load_dwordx4 v[174:177], v223, s[52:53]
	global_load_dwordx4 v[178:181], v224, s[52:53]
	global_load_dwordx4 v[182:185], v217, s[52:53] offset:64
	global_load_dwordx4 v[186:189], v218, s[52:53] offset:64
	global_load_dwordx4 v[190:193], v219, s[52:53] offset:64
	global_load_dwordx4 v[194:197], v220, s[52:53] offset:64
	global_load_dwordx4 v[240:243], v146, s[46:47] offset:64
	global_load_dwordx4 v[244:247], v146, s[48:49] offset:64
	global_load_dwordx4 v[198:201], v146, s[50:51] offset:64
	s_waitcnt vmcnt(14)
	s_cbranch_vccnz .Lres_r1_skip0
	v_sub_f32_e32 v153, v153, v130
	v_sub_f32_e32 v152, v152, v130
	v_sub_f32_e32 v151, v151, v130
	v_sub_f32_e32 v150, v150, v130
	v_pk_mul_f32 v[150:151], v[150:151], v[130:131] op_sel:[0,1]
	v_pk_mul_f32 v[152:153], v[152:153], v[130:131] op_sel:[0,1]
	v_pk_fma_f32 v[150:151], v[228:229], v[150:151], v[232:233]
	v_pk_fma_f32 v[152:153], v[230:231], v[152:153], v[234:235]

; __device__ __forceinline__ unsigned pk2(float lo, float hi) { const f2_t v = {lo, hi}; return __builtin_bit_cast(unsigned, __builtin_convertvector(v, bf2_t)); }
; template <bool OVL, bool PANEL = false, class Epi>
; __device__ __forceinline__ void gemm_phase(const bf16_t* __restrict__ A, long lda, const bf16_t* __restrict__ Bt, long ldb, int nM, int nN, int K,
;                                            const Epi& epi, bf16_t* shm, int w0) {
;     ...
;     asm volatile("s_nop 15\n\ts_nop 15" ::: "memory");
;   __device__ __forceinline__ void operator()(const f32x4 (&acc)[2][2][4][2], int pm, int pn, int wr_, int wc_, int fr_, int fq_, bf16_t* shm, int tid) const {
;     ...
; #pragma unroll
;     for (int ai = 0; ai < 2; ++ai)
; #pragma unroll
;       for (int bj = 0; bj < 2; ++bj)
; #pragma unroll
;         for (int m = 0; m < 4; ++m)
; #pragma unroll
;           for (int n = 0; n < 2; ++n) {
;             const f32x4 v = acc[ai][bj][m][n];
;             u32x2 w; w.x = pk2(v[0], v[1]); w.y = pk2(v[2], v[3]);
;             *(u32x2*)(Us + (ai * 128 + wr * 64 + m * 16 + fr + 1) * USTR + bj * 128 + wc * 32 + n * 16 + fq * 4) = w;
;           }
;     if (tid < 64) {
;       const int after = tid >> 5, c = (tid & 31) * 8;
;       u32x4 hv = {0, 0, 0, 0};
;       if (pm < 256) {
;         if (!after && (pm & 7) != 0) hv = *(const u32x4*)(HU + (long)((pm - 1) * 2 + 1) * 5632 + pn * 256 + c);
;         if (after && ((pm + 1) & 7) != 0) hv = *(const u32x4*)(HU + (long)((pm + 1) * 2) * 5632 + pn * 256 + c);
;       }
;       *(u32x4*)(Us + (after ? 257 : 0) * USTR + c) = hv;
.LBB0_391:
	v_readlane_b32 s10, v250, 0
	s_nop 11
	v_mbcnt_lo_u32_b32 v144, -1, 0
	v_mbcnt_hi_u32_b32 v144, -1, v144
	v_cvt_pk_bf16_f32 v90, v90, v91
	v_and_b32_e32 v0, 15, v144
	v_add_u32_e32 v143, s10, v144
	v_lshrrev_b32_e32 v145, 2, v143
	s_mov_b32 s10, 0xfffffc0
	v_ashrrev_i32_e32 v142, 4, v143
	v_and_or_b32 v145, v145, s10, v0
	s_movk_i32 s10, 0x210
	v_mul_lo_u32 v145, v145, s10
	v_lshlrev_b32_e32 v147, 3, v142
	v_add_u32_e32 v145, 16, v145
	v_and_b32_e32 v146, 0xc0, v143
	v_and_b32_e32 v147, 24, v147
	v_add3_u32 v145, v145, v146, v147
	v_cvt_pk_bf16_f32 v91, v92, v93
	v_add_u32_e32 v92, 0x6000, v145
	v_cvt_pk_bf16_f32 v58, v58, v59
	v_cvt_pk_bf16_f32 v59, v60, v61
	v_cvt_pk_bf16_f32 v50, v50, v51
	v_cvt_pk_bf16_f32 v51, v52, v53
	ds_write2_b64 v92, v[58:59], v[50:51] offset0:194 offset1:198
	v_add_u32_e32 v58, 0x10a10, v145
	v_cvt_pk_bf16_f32 v50, v78, v79
	v_cvt_pk_bf16_f32 v51, v80, v81
	v_cvt_pk_bf16_f32 v52, v74, v75
	v_cvt_pk_bf16_f32 v53, v76, v77
	ds_write2_b64 v58, v[50:51], v[52:53] offset1:4
	v_add_u32_e32 v58, 0x12b10, v145
	v_cvt_pk_bf16_f32 v50, v62, v63
	v_cvt_pk_bf16_f32 v51, v64, v65
	v_cvt_pk_bf16_f32 v52, v54, v55
	v_cvt_pk_bf16_f32 v53, v56, v57
	ds_write2_b64 v58, v[50:51], v[52:53] offset1:4
	v_add_u32_e32 v50, 0x14c10, v145
	v_cvt_pk_bf16_f32 v46, v46, v47
	v_cvt_pk_bf16_f32 v47, v48, v49
	v_cvt_pk_bf16_f32 v42, v42, v43
	v_cvt_pk_bf16_f32 v43, v44, v45
	ds_write2_b64 v50, v[46:47], v[42:43] offset1:4
	v_add_u32_e32 v42, 0x16d10, v145
	v_cvt_pk_bf16_f32 v38, v38, v39
	v_cvt_pk_bf16_f32 v39, v40, v41
	v_cvt_pk_bf16_f32 v34, v34, v35
	v_cvt_pk_bf16_f32 v35, v36, v37
	ds_write2_b64 v42, v[38:39], v[34:35] offset1:4
	v_add_u32_e32 v34, 0x10b10, v145
	v_cvt_pk_bf16_f32 v30, v30, v31
	v_cvt_pk_bf16_f32 v31, v32, v33
	v_cvt_pk_bf16_f32 v26, v26, v27
	v_cvt_pk_bf16_f32 v27, v28, v29
	v_cvt_pk_bf16_f32 v82, v82, v83
	v_cvt_pk_bf16_f32 v83, v84, v85
	ds_write2_b64 v34, v[30:31], v[26:27] offset1:4
	v_add_u32_e32 v26, 0x12c10, v145
	v_cvt_pk_bf16_f32 v22, v22, v23
	v_cvt_pk_bf16_f32 v23, v24, v25
	v_cvt_pk_bf16_f32 v18, v18, v19
	v_cvt_pk_bf16_f32 v19, v20, v21
	ds_write2_b64 v92, v[90:91], v[82:83] offset0:162 offset1:166
	v_cvt_pk_bf16_f32 v82, v106, v107
	v_cvt_pk_bf16_f32 v83, v108, v109
	v_cvt_pk_bf16_f32 v84, v98, v99
	v_cvt_pk_bf16_f32 v85, v100, v101
	ds_write2_b64 v26, v[22:23], v[18:19] offset1:4
	v_add_u32_e32 v18, 0x14d10, v145
	v_cvt_pk_bf16_f32 v14, v14, v15
	v_cvt_pk_bf16_f32 v15, v16, v17
	v_cvt_pk_bf16_f32 v10, v10, v11
	v_cvt_pk_bf16_f32 v11, v12, v13
	v_cvt_pk_bf16_f32 v126, v126, v127
	v_cvt_pk_bf16_f32 v127, v128, v129
	v_cvt_pk_bf16_f32 v122, v122, v123
	v_cvt_pk_bf16_f32 v123, v124, v125
	v_cvt_pk_bf16_f32 v118, v118, v119
	v_cvt_pk_bf16_f32 v119, v120, v121
	v_cvt_pk_bf16_f32 v114, v114, v115
	v_cvt_pk_bf16_f32 v115, v116, v117
	v_add_u32_e32 v116, 0x2000, v145
	v_cvt_pk_bf16_f32 v110, v110, v111
	v_cvt_pk_bf16_f32 v111, v112, v113
	v_cvt_pk_bf16_f32 v102, v102, v103
	v_cvt_pk_bf16_f32 v103, v104, v105
	v_add_u32_e32 v104, 0x4000, v145
	ds_write2_b64 v145, v[82:83], v[84:85] offset0:98 offset1:102
	v_cvt_pk_bf16_f32 v82, v94, v95
	v_cvt_pk_bf16_f32 v83, v96, v97
	v_cvt_pk_bf16_f32 v84, v86, v87
	v_cvt_pk_bf16_f32 v85, v88, v89
	v_cvt_pk_bf16_f32 v70, v70, v71
	v_cvt_pk_bf16_f32 v71, v72, v73
	v_cvt_pk_bf16_f32 v66, v66, v67
	v_cvt_pk_bf16_f32 v67, v68, v69
	ds_write2_b64 v18, v[14:15], v[10:11] offset1:4
	v_add_u32_e32 v10, 0x16e10, v145
	v_cvt_pk_bf16_f32 v6, v6, v7
	v_cvt_pk_bf16_f32 v7, v8, v9
	v_cvt_pk_bf16_f32 v2, v2, v3
	v_cvt_pk_bf16_f32 v3, v4, v5
	v_cmp_gt_i32_e32 vcc, 64, v143
	ds_write2_b64 v145, v[126:127], v[122:123] offset0:66 offset1:70
	ds_write2_b64 v116, v[118:119], v[114:115] offset0:98 offset1:102
	ds_write2_b64 v104, v[110:111], v[102:103] offset0:130 offset1:134
	ds_write2_b64 v116, v[82:83], v[84:85] offset0:130 offset1:134
	ds_write2_b64 v104, v[70:71], v[66:67] offset0:162 offset1:166
	ds_write2_b64 v10, v[6:7], v[2:3] offset1:4
	s_lshl_b32 s98, s24, 7
	v_lshl_or_b32 v82, v0, 3, s98
	v_ashrrev_i32_e32 v83, 31, v82
	v_lshlrev_b64 v[22:23], 2, v[82:83]
	v_lshl_add_u64 v[2:3], s[14:15], 0, v[22:23]
	v_lshl_add_u64 v[10:11], s[88:89], 0, v[22:23]
	global_load_dwordx4 v[6:9], v[2:3], off offset:16
	global_load_dwordx4 v[38:41], v[2:3], off
	s_nop 0
	global_load_dwordx4 v[2:5], v[10:11], off offset:16
	global_load_dwordx4 v[34:37], v[10:11], off
	v_lshl_add_u64 v[10:11], s[90:91], 0, v[22:23]
	v_lshl_add_u64 v[18:19], s[26:27], 0, v[22:23]
	global_load_dwordx4 v[14:17], v[10:11], off offset:16
	global_load_dwordx4 v[46:49], v[10:11], off
	s_nop 0
	global_load_dwordx4 v[10:13], v[18:19], off offset:16
	global_load_dwordx4 v[42:45], v[18:19], off
	v_lshl_add_u64 v[18:19], s[62:63], 0, v[22:23]
	v_lshl_add_u64 v[24:25], s[0:1], 0, v[22:23]
	global_load_dwordx4 v[26:29], v[18:19], off offset:16
	global_load_dwordx4 v[58:61], v[18:19], off
	s_nop 0
	global_load_dwordx4 v[18:21], v[24:25], off offset:16
	global_load_dwordx4 v[50:53], v[24:25], off
	v_lshl_add_u64 v[24:25], s[40:41], 0, v[22:23]
	v_lshl_add_u64 v[54:55], s[4:5], 0, v[22:23]
	global_load_dwordx4 v[30:33], v[24:25], off offset:16
	global_load_dwordx4 v[62:65], v[24:25], off
	s_nop 0
	global_load_dwordx4 v[22:25], v[54:55], off offset:16
	s_nop 0
	global_load_dwordx4 v[54:57], v[54:55], off
	s_and_saveexec_b64 s[42:43], vcc
	s_cbranch_execz .LBB0_400
	v_lshlrev_b32_e32 v206, 3, v144
	v_and_b32_e32 v210, 0xf8, v206
	v_mov_b32_e32 v209, 0
	s_cmpk_gt_i32 s25, 0xff
	v_cmp_gt_u32_e64 s[10:11], 32, v143
	v_mov_b32_e32 v208, 0
	v_mov_b32_e32 v207, 0
	v_mov_b32_e32 v206, 0
	s_cbranch_scc1 .LBB0_399
	s_and_b32 s28, s25, 7
	s_cmp_lg_u32 s28, 0
	s_cselect_b64 s[28:29], -1, 0
	v_cmp_lt_u32_e32 vcc, 31, v143
	s_and_b64 s[28:29], s[28:29], s[10:11]
	v_mov_b32_e32 v206, 0
	v_mov_b32_e32 v207, 0
	v_mov_b32_e32 v208, 0
	v_mov_b32_e32 v209, 0
	s_and_saveexec_b64 s[10:11], s[28:29]
	s_cbranch_execz .LBB0_395
	s_lshl_b32 s28, s25, 1
	s_add_i32 s28, s28, -1
	v_readlane_b32 s44, v252, 20
	s_mul_hi_i32 s29, s28, 0x2c00
	s_mulk_i32 s28, 0x2c00
	v_readlane_b32 s56, v252, 32
	v_readlane_b32 s57, v252, 33
	s_add_u32 s30, s56, s28
	s_addc_u32 s31, s57, s29
	s_lshl_b64 s[28:29], s[6:7], 1
	s_add_u32 s28, s30, s28
	s_addc_u32 s29, s31, s29
	v_lshlrev_b32_e32 v206, 1, v210
	global_load_dwordx4 v[206:209], v206, s[28:29]
	v_readlane_b32 s45, v252, 21
	v_readlane_b32 s46, v252, 22
	v_readlane_b32 s47, v252, 23
	v_readlane_b32 s48, v252, 24
	v_readlane_b32 s49, v252, 25
	v_readlane_b32 s50, v252, 26
	v_readlane_b32 s51, v252, 27
	v_readlane_b32 s52, v252, 28
	v_readlane_b32 s53, v252, 29
	v_readlane_b32 s54, v252, 30
	v_readlane_b32 s55, v252, 31
	v_readlane_b32 s58, v252, 34
	v_readlane_b32 s59, v252, 35

; __device__ __forceinline__ unsigned pk2(float lo, float hi) { const f2_t v = {lo, hi}; return __builtin_bit_cast(unsigned, __builtin_convertvector(v, bf2_t)); }
; #define EPI_LOOP for (int ai = 0; ai < 2; ++ai) for (int bj = 0; bj < 2; ++bj) for (int m = 0; m < 4; ++m) for (int n = 0; n < 2; ++n)
; template <bool OVL, bool PANEL = false, class Epi>
; __device__ __forceinline__ void gemm_phase(const bf16_t* __restrict__ A, long lda, const bf16_t* __restrict__ Bt, long ldb, int nM, int nN, int K,
;                                            const Epi& epi, bf16_t* shm, int w0) {
;     ...
;     asm volatile("s_nop 15\n\ts_nop 15" ::: "memory");
;   __device__ __forceinline__ void operator()(const f32x4 (&acc)[2][2][4][2], int pm, int pn, int wr, int wc, int fr, int fq, bf16_t* shm, int tid) const {
; #pragma unroll
;     EPI_LOOP { EPI_RC
;       u32x2 w; w.x = pk2(v[0], v[1]); w.y = pk2(v[2], v[3]); *(u32x2*)(U + (long)row * 5632 + col) = w; }
;   }
.LBB0_406:
	v_readlane_b32 s40, v252, 20
	v_readlane_b32 s52, v252, 32
	v_readlane_b32 s53, v252, 33
	s_nop 11
	v_mbcnt_lo_u32_b32 v0, -1, 0
	v_mbcnt_hi_u32_b32 v0, -1, v0
	v_lshl_add_u32 v146, s20, 8, v141
	v_cvt_pk_bf16_f32 v126, v126, v127
	v_cvt_pk_bf16_f32 v127, v128, v129
	v_mov_b64_e32 v[128:129], s[52:53]
	s_movk_i32 s0, 0x2c00
	v_mad_i64_i32 v[144:145], s[10:11], v146, s0, v[128:129]
	v_lshl_or_b32 v0, s18, 9, v142
	v_lshl_add_u64 v[144:145], v[144:145], 0, v[0:1]
	global_store_dwordx2 v[144:145], v[126:127], off
	v_cvt_pk_bf16_f32 v122, v122, v123
	v_cvt_pk_bf16_f32 v123, v124, v125
	global_store_dwordx2 v[144:145], v[122:123], off offset:32
	v_or_b32_e32 v122, 16, v146
	v_cvt_pk_bf16_f32 v118, v118, v119
	v_cvt_pk_bf16_f32 v119, v120, v121
	v_mad_i64_i32 v[120:121], s[10:11], v122, s0, v[128:129]
	v_lshl_add_u64 v[120:121], v[120:121], 0, v[0:1]
	global_store_dwordx2 v[120:121], v[118:119], off
	v_cvt_pk_bf16_f32 v114, v114, v115
	v_cvt_pk_bf16_f32 v115, v116, v117
	global_store_dwordx2 v[120:121], v[114:115], off offset:32
	v_or_b32_e32 v114, 32, v146
	v_cvt_pk_bf16_f32 v110, v110, v111
	v_cvt_pk_bf16_f32 v111, v112, v113
	v_mad_i64_i32 v[112:113], s[10:11], v114, s0, v[128:129]
	v_lshl_add_u64 v[112:113], v[112:113], 0, v[0:1]
	global_store_dwordx2 v[112:113], v[110:111], off
	v_cvt_pk_bf16_f32 v106, v106, v107
	v_cvt_pk_bf16_f32 v107, v108, v109
	global_store_dwordx2 v[112:113], v[106:107], off offset:32
	v_or_b32_e32 v106, 48, v146
	v_cvt_pk_bf16_f32 v98, v98, v99
	v_cvt_pk_bf16_f32 v99, v100, v101
	v_mad_i64_i32 v[100:101], s[10:11], v106, s0, v[128:129]
	v_lshl_add_u64 v[100:101], v[100:101], 0, v[0:1]
	global_store_dwordx2 v[100:101], v[98:99], off
	v_cvt_pk_bf16_f32 v90, v90, v91
	v_cvt_pk_bf16_f32 v91, v92, v93
	global_store_dwordx2 v[100:101], v[90:91], off offset:32
	v_cvt_pk_bf16_f32 v90, v102, v103
	v_cvt_pk_bf16_f32 v91, v104, v105
	global_store_dwordx2 v[144:145], v[90:91], off offset:256
	v_cvt_pk_bf16_f32 v90, v94, v95
	v_cvt_pk_bf16_f32 v91, v96, v97
	global_store_dwordx2 v[144:145], v[90:91], off offset:288
	v_cvt_pk_bf16_f32 v86, v86, v87
	v_cvt_pk_bf16_f32 v87, v88, v89
	global_store_dwordx2 v[120:121], v[86:87], off offset:256
	v_cvt_pk_bf16_f32 v82, v82, v83
	v_cvt_pk_bf16_f32 v83, v84, v85
	global_store_dwordx2 v[120:121], v[82:83], off offset:288
	v_cvt_pk_bf16_f32 v78, v78, v79
	v_cvt_pk_bf16_f32 v79, v80, v81
	global_store_dwordx2 v[112:113], v[78:79], off offset:256
	v_cvt_pk_bf16_f32 v70, v70, v71
	v_cvt_pk_bf16_f32 v71, v72, v73
	global_store_dwordx2 v[112:113], v[70:71], off offset:288
	v_cvt_pk_bf16_f32 v66, v66, v67
	v_cvt_pk_bf16_f32 v67, v68, v69
	v_cvt_pk_bf16_f32 v58, v58, v59
	v_cvt_pk_bf16_f32 v59, v60, v61
	v_add_u32_e32 v60, 0x80, v146
	global_store_dwordx2 v[100:101], v[66:67], off offset:256
	v_mad_i64_i32 v[60:61], s[10:11], v60, s0, v[128:129]
	global_store_dwordx2 v[100:101], v[58:59], off offset:288
	v_cvt_pk_bf16_f32 v58, v74, v75
	v_cvt_pk_bf16_f32 v59, v76, v77
	v_lshl_add_u64 v[60:61], v[60:61], 0, v[0:1]
	global_store_dwordx2 v[60:61], v[58:59], off
	v_cvt_pk_bf16_f32 v58, v62, v63
	v_cvt_pk_bf16_f32 v59, v64, v65
	global_store_dwordx2 v[60:61], v[58:59], off offset:32
	v_add_u32_e32 v58, 0x90, v146
	v_cvt_pk_bf16_f32 v54, v54, v55
	v_cvt_pk_bf16_f32 v55, v56, v57
	v_mad_i64_i32 v[56:57], s[10:11], v58, s0, v[128:129]
	v_lshl_add_u64 v[56:57], v[56:57], 0, v[0:1]
	global_store_dwordx2 v[56:57], v[54:55], off
	v_cvt_pk_bf16_f32 v50, v50, v51
	v_cvt_pk_bf16_f32 v51, v52, v53
	global_store_dwordx2 v[56:57], v[50:51], off offset:32
	v_add_u32_e32 v50, 0xa0, v146
	v_cvt_pk_bf16_f32 v46, v46, v47
	v_cvt_pk_bf16_f32 v47, v48, v49
	v_mad_i64_i32 v[48:49], s[10:11], v50, s0, v[128:129]
	v_lshl_add_u64 v[48:49], v[48:49], 0, v[0:1]
	global_store_dwordx2 v[48:49], v[46:47], off
	v_cvt_pk_bf16_f32 v42, v42, v43
	v_cvt_pk_bf16_f32 v43, v44, v45
	global_store_dwordx2 v[48:49], v[42:43], off offset:32
	v_add_u32_e32 v42, 0xb0, v146
	v_cvt_pk_bf16_f32 v38, v38, v39
	v_cvt_pk_bf16_f32 v39, v40, v41
	v_mad_i64_i32 v[40:41], s[10:11], v42, s0, v[128:129]
	v_lshl_add_u64 v[40:41], v[40:41], 0, v[0:1]
	global_store_dwordx2 v[40:41], v[38:39], off
	v_cvt_pk_bf16_f32 v34, v34, v35
	v_cvt_pk_bf16_f32 v35, v36, v37
	global_store_dwordx2 v[40:41], v[34:35], off offset:32
	v_cvt_pk_bf16_f32 v30, v30, v31
	v_cvt_pk_bf16_f32 v31, v32, v33
	global_store_dwordx2 v[60:61], v[30:31], off offset:256
	v_cvt_pk_bf16_f32 v26, v26, v27
	v_cvt_pk_bf16_f32 v27, v28, v29
	global_store_dwordx2 v[60:61], v[26:27], off offset:288
	v_cvt_pk_bf16_f32 v22, v22, v23
	v_cvt_pk_bf16_f32 v23, v24, v25
	global_store_dwordx2 v[56:57], v[22:23], off offset:256
	v_cvt_pk_bf16_f32 v18, v18, v19
	v_cvt_pk_bf16_f32 v19, v20, v21
	global_store_dwordx2 v[56:57], v[18:19], off offset:288
	v_cvt_pk_bf16_f32 v14, v14, v15
	v_cvt_pk_bf16_f32 v15, v16, v17
	global_store_dwordx2 v[48:49], v[14:15], off offset:256
	v_cvt_pk_bf16_f32 v10, v10, v11
	v_cvt_pk_bf16_f32 v11, v12, v13
	global_store_dwordx2 v[48:49], v[10:11], off offset:288
	v_cvt_pk_bf16_f32 v6, v6, v7
	v_cvt_pk_bf16_f32 v7, v8, v9
	global_store_dwordx2 v[40:41], v[6:7], off offset:256
	v_cvt_pk_bf16_f32 v2, v2, v3
	v_cvt_pk_bf16_f32 v3, v4, v5
	global_store_dwordx2 v[40:41], v[2:3], off offset:288
	s_waitcnt vmcnt(0)
	s_andn2_b64 vcc, exec, s[8:9]
	s_mov_b32 s18, s1
	s_mov_b32 s20, s12
	v_readlane_b32 s41, v252, 21
	v_readlane_b32 s42, v252, 22
	v_readlane_b32 s43, v252, 23
	v_readlane_b32 s44, v252, 24
	v_readlane_b32 s45, v252, 25
	v_readlane_b32 s46, v252, 26
	v_readlane_b32 s47, v252, 27
	v_readlane_b32 s48, v252, 28
	v_readlane_b32 s49, v252, 29
	v_readlane_b32 s50, v252, 30
	v_readlane_b32 s51, v252, 31
	v_readlane_b32 s54, v252, 34
	v_readlane_b32 s55, v252, 35
	s_cbranch_vccz .LBB0_421

; template <bool OVL, bool PANEL = false, class Epi>
; __device__ __forceinline__ void gemm_phase(const bf16_t* __restrict__ A, long lda, const bf16_t* __restrict__ Bt, long ldb, int nM, int nN, int K,
;                                            const Epi& epi, bf16_t* shm, int w0) {
;     ...
;     asm volatile("s_nop 15\n\ts_nop 15" ::: "memory");
;   __device__ __forceinline__ void operator()(f32x4 (&acc)[2][2][4][2], int pm, int pn, int wr_, int wc_, int fr_, int fq_, bf16_t* shm, int tid) const {
;     ...
;     const float* Xr = (!fdown && l == 0) ? (pm < 256 ? p.x : p.ctx - (long)NLAT * DM) : (const float*)X;
;     const long bio = (long)row_bi(pm * 256) * 6144;
;     f2_t* red = (f2_t*)((char*)shm + 128 * 1024);
;     f2_t* rst = (f2_t*)((char*)shm + 128 * 1024 + 8192);
;     float s1[8], s2[8];
; #pragma unroll
;     for (int i = 0; i < 8; ++i) { s1[i] = 0.f; s2[i] = 0.f; }
; #pragma unroll
;     for (int bj = 0; bj < 2; ++bj)
; #pragma unroll
;       for (int n = 0; n < 2; ++n) {
;         asm volatile("" ::: "memory");
;         const int col = pn * 256 + bj * 128 + wc * 32 + n * 16 + fq * 4;
;         f32x4 lg = {1.f, 1.f, 1.f, 1.f}, lb = {0.f, 0.f, 0.f, 0.f};
;         if (stats) { lg = *(const f32x4*)(lng + col); lb = *(const f32x4*)(lnb + col); }
;         const f32x4 gv = *(const f32x4*)(g + bio + col);
; #pragma unroll
;         for (int ai = 0; ai < 2; ++ai)
; #pragma unroll
;           for (int m = 0; m < 4; ++m) {
;             const int row = pm * 256 + ai * 128 + wr * 64 + m * 16 + fr;
;             const f32x4 v = acc[ai][bj][m][n];
;             f32x4* xp = (f32x4*)(X + (long)row * DM + col);
;             f32x4 xv = *(const f32x4*)(Xr + (long)row * DM + col);
;             if (stats) { const float mu = stats[2 * row], rs = stats[2 * row + 1]; xv = (xv - mu) * rs * lg + lb; }
;             xv = xv * ALPHA + gv * v; *xp = xv;
.LBB0_477:
	v_readlane_b32 s1, v250, 0
	s_nop 11
	v_mbcnt_lo_u32_b32 v138, -1, 0
	v_mbcnt_hi_u32_b32 v138, -1, v138
	s_lshl_b32 s0, s25, 8
	v_bfe_u32 v244, v138, 4, 2
	v_add_u32_e32 v148, s1, v138
	v_bfe_u32 v243, v148, 6, 2
	v_lshlrev_b32_e32 v0, 5, v243
	v_lshlrev_b32_e32 v130, 2, v244
	v_or3_b32 v0, v0, v130, s0
	v_cndmask_b32_e64 v130, 0, 1, s[66:67]
	v_lshlrev_b64 v[146:147], 2, v[0:1]
	v_cmp_ne_u32_e64 s[8:9], 1, v130
	s_andn2_b64 vcc, exec, s[66:67]
	v_lshl_add_u64 v[150:151], s[84:85], 0, v[146:147]
	v_lshl_add_u64 v[152:153], s[86:87], 0, v[146:147]
	s_cmpk_lt_i32 s4, 0x100
	v_readlane_b32 s44, v252, 49
	v_readlane_b32 s0, v251, 5
	v_readlane_b32 s45, v252, 50
	s_cselect_b32 s5, s44, s0
	v_readlane_b32 s0, v251, 6
	s_cselect_b32 s12, s45, s0
	s_and_b64 s[0:1], s[76:77], exec
	v_readlane_b32 s48, v252, 24
	v_readlane_b32 s49, v252, 25
	s_cselect_b32 s1, s12, s49
	s_cselect_b32 s0, s5, s48
	s_mov_b64 s[52:53], s[0:1]
	s_mov_b64 s[54:55], s[48:49]
	s_min_i32 s5, s82, 0x10000
	s_ashr_i32 s5, s5, 11
	s_mul_hi_i32 s7, s5, 0x1800
	s_mul_i32 s6, s5, 0x1800
	s_lshl_b64 s[6:7], s[6:7], 2
	v_and_b32_e32 v149, 15, v138
	v_ashrrev_i32_e32 v138, 2, v148
	v_and_b32_e32 v242, 0xffffffc0, v138
	v_or_b32_e32 v138, s82, v149
	v_add_u32_e32 v247, v242, v138
	s_add_u32 s50, s22, s6
	s_addc_u32 s51, s23, s7
	s_mov_b64 s[44:45], s[10:11]
	s_and_b64 vcc, exec, s[8:9]
	s_cselect_b32 s44, s54, s44
	s_cselect_b32 s45, s55, s45
	s_cselect_b32 s46, s50, s84
	s_cselect_b32 s47, s51, s85
	s_cselect_b32 s48, s50, s86
	s_cselect_b32 s49, s51, s87
	v_lshlrev_b32_e32 v246, 3, v247
	v_lshlrev_b32_e32 v218, 12, v247
	v_add_u32_e32 v218, v218, v146
	v_add_u32_e32 v219, 0x10000, v218
	v_add_u32_e32 v224, 0x20000, v218
	v_add_u32_e32 v225, 0x30000, v218
	v_add_u32_e32 v227, 0x80000, v218
	v_add_u32_e32 v232, 0x90000, v218
	v_add_u32_e32 v233, 0xa0000, v218
	v_add_u32_e32 v245, 0xb0000, v218
	global_load_dwordx2 v[130:131], v246, s[44:45]
	global_load_dwordx2 v[132:133], v246, s[44:45] offset:128
	global_load_dwordx2 v[134:135], v246, s[44:45] offset:256
	global_load_dwordx2 v[136:137], v246, s[44:45] offset:384
	global_load_dwordx2 v[138:139], v246, s[44:45] offset:1024
	global_load_dwordx2 v[140:141], v246, s[44:45] offset:1152
	global_load_dwordx2 v[142:143], v246, s[44:45] offset:1280
	global_load_dwordx2 v[144:145], v246, s[44:45] offset:1408
	global_load_dwordx4 v[198:201], v146, s[46:47]
	global_load_dwordx4 v[202:205], v146, s[48:49]
	global_load_dwordx4 v[206:209], v146, s[50:51]
	global_load_dwordx4 v[150:153], v218, s[52:53]
	global_load_dwordx4 v[154:157], v219, s[52:53]
	global_load_dwordx4 v[158:161], v224, s[52:53]
	global_load_dwordx4 v[162:165], v225, s[52:53]
	global_load_dwordx4 v[166:169], v227, s[52:53]
	global_load_dwordx4 v[170:173], v232, s[52:53]
	global_load_dwordx4 v[174:177], v233, s[52:53]
	global_load_dwordx4 v[178:181], v245, s[52:53]
	global_load_dwordx4 v[182:185], v218, s[52:53] offset:64
	global_load_dwordx4 v[186:189], v219, s[52:53] offset:64
	global_load_dwordx4 v[190:193], v224, s[52:53] offset:64
	global_load_dwordx4 v[194:197], v225, s[52:53] offset:64
	global_load_dwordx4 v[210:213], v146, s[46:47] offset:64
	global_load_dwordx4 v[214:217], v146, s[48:49] offset:64
	global_load_dwordx4 v[228:231], v146, s[50:51] offset:64
	s_waitcnt vmcnt(14)
	s_cbranch_vccnz .Lres_r2_skip0
	v_sub_f32_e32 v153, v153, v130
	v_sub_f32_e32 v152, v152, v130
	v_sub_f32_e32 v151, v151, v130
	v_sub_f32_e32 v150, v150, v130
	v_pk_mul_f32 v[150:151], v[150:151], v[130:131] op_sel:[0,1]
	v_pk_mul_f32 v[152:153], v[152:153], v[130:131] op_sel:[0,1]
	v_pk_fma_f32 v[150:151], v[198:199], v[150:151], v[202:203]
	v_pk_fma_f32 v[152:153], v[200:201], v[152:153], v[204:205]

; __device__ __forceinline__ unsigned pk2(float lo, float hi) { const f2_t v = {lo, hi}; return __builtin_bit_cast(unsigned, __builtin_convertvector(v, bf2_t)); }
; #define EPI_LOOP for (int ai = 0; ai < 2; ++ai) for (int bj = 0; bj < 2; ++bj) for (int m = 0; m < 4; ++m) for (int n = 0; n < 2; ++n)
; template <bool OVL, bool PANEL = false, class Epi>
; __device__ __forceinline__ void gemm_phase(const bf16_t* __restrict__ A, long lda, const bf16_t* __restrict__ Bt, long ldb, int nM, int nN, int K,
;                                            const Epi& epi, bf16_t* shm, int w0) {
;     ...
;     asm volatile("s_nop 15\n\ts_nop 15" ::: "memory");
;   __device__ __forceinline__ void operator()(const f32x4 (&acc)[2][2][4][2], int pm, int pn, int wr, int wc, int fr, int fq, bf16_t* shm, int tid) const {
; #pragma unroll
;     EPI_LOOP { EPI_RC
;       const float s = rstd[2 * row] * (0.10206207261596577f * 1.4426950408889634f);
;       u32x2 w; w.x = pk2(v[0] * s, v[1] * s); w.y = pk2(v[2] * s, v[3] * s); *(u32x2*)(Q + (long)row * 768 + col) = w; }
.LBB0_682:
	v_add_u32_e32 v144, s23, v248
	v_lshlrev_b32_e32 v130, 1, v144
	v_readlane_b32 s40, v253, 7
	v_ashrrev_i32_e32 v131, 31, v130
	v_readlane_b32 s52, v253, 19
	v_readlane_b32 s53, v253, 20
	s_nop 11
	v_mbcnt_lo_u32_b32 v0, -1, 0
	v_mbcnt_hi_u32_b32 v0, -1, v0
	v_readlane_b32 s41, v253, 8
	v_or_b32_e32 v132, s12, v249
	v_lshl_add_u64 v[140:141], v[130:131], 2, s[52:53]
	v_mov_b64_e32 v[130:131], s[40:41]
	s_movk_i32 s12, 0x600
	v_ashrrev_i32_e32 v133, 31, v132
	v_mad_i64_i32 v[142:143], s[10:11], v144, s12, v[130:131]
	v_lshlrev_b64 v[132:133], 1, v[132:133]
	v_lshl_add_u64 v[142:143], v[142:143], 0, v[132:133]
	s_andn2_b64 vcc, exec, s[8:9]
	global_load_dword v150, v[140:141], off
	global_load_dword v151, v[140:141], off offset:128
	global_load_dword v152, v[140:141], off offset:256
	global_load_dword v153, v[140:141], off offset:384
	global_load_dword v154, v[140:141], off offset:1024
	global_load_dword v155, v[140:141], off offset:1152
	global_load_dword v156, v[140:141], off offset:1280
	global_load_dword v157, v[140:141], off offset:1408
	s_mov_b32 s43, 0
	s_mov_b32 s42, 0x6000
	v_lshl_add_u64 v[160:161], v[142:143], 0, s[42:43]
	s_mov_b32 s42, 0xc000
	v_lshl_add_u64 v[162:163], v[142:143], 0, s[42:43]
	s_mov_b32 s42, 0x12000
	v_lshl_add_u64 v[164:165], v[142:143], 0, s[42:43]
	s_mov_b32 s42, 0x30000
	v_lshl_add_u64 v[166:167], v[142:143], 0, s[42:43]
	s_mov_b32 s42, 0x36000
	v_lshl_add_u64 v[168:169], v[142:143], 0, s[42:43]
	s_mov_b32 s42, 0x3c000
	v_lshl_add_u64 v[170:171], v[142:143], 0, s[42:43]
	s_mov_b32 s42, 0x42000
	v_lshl_add_u64 v[172:173], v[142:143], 0, s[42:43]
	s_waitcnt vmcnt(0)
	v_mul_f32_e32 v150, 0x3e16c740, v150
	v_mul_f32_e32 v151, 0x3e16c740, v151
	v_mul_f32_e32 v152, 0x3e16c740, v152
	v_mul_f32_e32 v153, 0x3e16c740, v153
	v_mul_f32_e32 v154, 0x3e16c740, v154
	v_mul_f32_e32 v155, 0x3e16c740, v155
	v_mul_f32_e32 v156, 0x3e16c740, v156
	v_mul_f32_e32 v157, 0x3e16c740, v157
	v_and_b32_e32 v196, 4, v249
	v_mul_u32_u24_e32 v196, 6, v196
	v_mov_b32_e32 v197, v1
	v_lshl_add_u64 v[142:143], v[142:143], 0, v[196:197]
	v_lshl_add_u64 v[160:161], v[160:161], 0, v[196:197]
	v_lshl_add_u64 v[162:163], v[162:163], 0, v[196:197]
	v_lshl_add_u64 v[164:165], v[164:165], 0, v[196:197]
	v_lshl_add_u64 v[166:167], v[166:167], 0, v[196:197]
	v_lshl_add_u64 v[168:169], v[168:169], 0, v[196:197]
	v_lshl_add_u64 v[170:171], v[170:171], 0, v[196:197]
	v_lshl_add_u64 v[172:173], v[172:173], 0, v[196:197]
	v_pk_mul_f32 v[126:127], v[126:127], v[150:151] op_sel_hi:[1,0]
	v_pk_mul_f32 v[128:129], v[128:129], v[150:151] op_sel_hi:[1,0]
	v_pk_mul_f32 v[122:123], v[122:123], v[150:151] op_sel_hi:[1,0]
	v_pk_mul_f32 v[124:125], v[124:125], v[150:151] op_sel_hi:[1,0]
	v_pk_mul_f32 v[118:119], v[118:119], v[150:151] op_sel:[0,1]
	v_pk_mul_f32 v[120:121], v[120:121], v[150:151] op_sel:[0,1]
	v_pk_mul_f32 v[114:115], v[114:115], v[150:151] op_sel:[0,1]
	v_pk_mul_f32 v[116:117], v[116:117], v[150:151] op_sel:[0,1]
	v_pk_mul_f32 v[110:111], v[110:111], v[152:153] op_sel_hi:[1,0]
	v_pk_mul_f32 v[112:113], v[112:113], v[152:153] op_sel_hi:[1,0]
	v_pk_mul_f32 v[106:107], v[106:107], v[152:153] op_sel_hi:[1,0]
	v_pk_mul_f32 v[108:109], v[108:109], v[152:153] op_sel_hi:[1,0]
	v_pk_mul_f32 v[102:103], v[102:103], v[152:153] op_sel:[0,1]
	v_pk_mul_f32 v[104:105], v[104:105], v[152:153] op_sel:[0,1]
	v_pk_mul_f32 v[98:99], v[98:99], v[152:153] op_sel:[0,1]
	v_pk_mul_f32 v[100:101], v[100:101], v[152:153] op_sel:[0,1]
	v_pk_mul_f32 v[94:95], v[94:95], v[150:151] op_sel_hi:[1,0]
	v_pk_mul_f32 v[96:97], v[96:97], v[150:151] op_sel_hi:[1,0]
	v_pk_mul_f32 v[90:91], v[90:91], v[150:151] op_sel_hi:[1,0]
	v_pk_mul_f32 v[92:93], v[92:93], v[150:151] op_sel_hi:[1,0]
	v_pk_mul_f32 v[86:87], v[86:87], v[150:151] op_sel:[0,1]
	v_pk_mul_f32 v[88:89], v[88:89], v[150:151] op_sel:[0,1]
	v_pk_mul_f32 v[82:83], v[82:83], v[150:151] op_sel:[0,1]
	v_pk_mul_f32 v[84:85], v[84:85], v[150:151] op_sel:[0,1]
	v_pk_mul_f32 v[78:79], v[78:79], v[152:153] op_sel_hi:[1,0]
	v_pk_mul_f32 v[80:81], v[80:81], v[152:153] op_sel_hi:[1,0]
	v_pk_mul_f32 v[74:75], v[74:75], v[152:153] op_sel_hi:[1,0]
	v_pk_mul_f32 v[76:77], v[76:77], v[152:153] op_sel_hi:[1,0]
	v_pk_mul_f32 v[70:71], v[70:71], v[152:153] op_sel:[0,1]
	v_pk_mul_f32 v[72:73], v[72:73], v[152:153] op_sel:[0,1]
	v_pk_mul_f32 v[66:67], v[66:67], v[152:153] op_sel:[0,1]
	v_pk_mul_f32 v[68:69], v[68:69], v[152:153] op_sel:[0,1]
	v_pk_mul_f32 v[62:63], v[62:63], v[154:155] op_sel_hi:[1,0]
	v_pk_mul_f32 v[64:65], v[64:65], v[154:155] op_sel_hi:[1,0]
	v_pk_mul_f32 v[58:59], v[58:59], v[154:155] op_sel_hi:[1,0]
	v_pk_mul_f32 v[60:61], v[60:61], v[154:155] op_sel_hi:[1,0]
	v_pk_mul_f32 v[54:55], v[54:55], v[154:155] op_sel:[0,1]
	v_pk_mul_f32 v[56:57], v[56:57], v[154:155] op_sel:[0,1]
	v_pk_mul_f32 v[50:51], v[50:51], v[154:155] op_sel:[0,1]
	v_pk_mul_f32 v[52:53], v[52:53], v[154:155] op_sel:[0,1]
	v_pk_mul_f32 v[46:47], v[46:47], v[156:157] op_sel_hi:[1,0]
	v_pk_mul_f32 v[48:49], v[48:49], v[156:157] op_sel_hi:[1,0]
	v_pk_mul_f32 v[42:43], v[42:43], v[156:157] op_sel_hi:[1,0]
	v_pk_mul_f32 v[44:45], v[44:45], v[156:157] op_sel_hi:[1,0]
	v_pk_mul_f32 v[38:39], v[38:39], v[156:157] op_sel:[0,1]
	v_pk_mul_f32 v[40:41], v[40:41], v[156:157] op_sel:[0,1]
; __device__ __forceinline__ unsigned pk2(float lo, float hi) { const f2_t v = {lo, hi}; return __builtin_bit_cast(unsigned, __builtin_convertvector(v, bf2_t)); }
; #define EPI_LOOP for (int ai = 0; ai < 2; ++ai) for (int bj = 0; bj < 2; ++bj) for (int m = 0; m < 4; ++m) for (int n = 0; n < 2; ++n)
;   __device__ __forceinline__ void operator()(const f32x4 (&acc)[2][2][4][2], int pm, int pn, int wr, int wc, int fr, int fq, bf16_t* shm, int tid) const {
;     ...
;     EPI_LOOP { EPI_RC
;       const float s = rstd[2 * row] * (0.10206207261596577f * 1.4426950408889634f);
;       u32x2 w; w.x = pk2(v[0] * s, v[1] * s); w.y = pk2(v[2] * s, v[3] * s); *(u32x2*)(Q + (long)row * 768 + col) = w; }
	v_pk_mul_f32 v[34:35], v[34:35], v[156:157] op_sel:[0,1]
	v_pk_mul_f32 v[36:37], v[36:37], v[156:157] op_sel:[0,1]
	v_pk_mul_f32 v[30:31], v[30:31], v[154:155] op_sel_hi:[1,0]
	v_pk_mul_f32 v[32:33], v[32:33], v[154:155] op_sel_hi:[1,0]
	v_pk_mul_f32 v[26:27], v[26:27], v[154:155] op_sel_hi:[1,0]
	v_pk_mul_f32 v[28:29], v[28:29], v[154:155] op_sel_hi:[1,0]
	v_pk_mul_f32 v[22:23], v[22:23], v[154:155] op_sel:[0,1]
	v_pk_mul_f32 v[24:25], v[24:25], v[154:155] op_sel:[0,1]
	v_pk_mul_f32 v[18:19], v[18:19], v[154:155] op_sel:[0,1]
	v_pk_mul_f32 v[20:21], v[20:21], v[154:155] op_sel:[0,1]
	v_pk_mul_f32 v[14:15], v[14:15], v[156:157] op_sel_hi:[1,0]
	v_pk_mul_f32 v[16:17], v[16:17], v[156:157] op_sel_hi:[1,0]
	v_pk_mul_f32 v[10:11], v[10:11], v[156:157] op_sel_hi:[1,0]
	v_pk_mul_f32 v[12:13], v[12:13], v[156:157] op_sel_hi:[1,0]
	v_pk_mul_f32 v[6:7], v[6:7], v[156:157] op_sel:[0,1]
	v_pk_mul_f32 v[8:9], v[8:9], v[156:157] op_sel:[0,1]
	v_pk_mul_f32 v[2:3], v[2:3], v[156:157] op_sel:[0,1]
	v_pk_mul_f32 v[4:5], v[4:5], v[156:157] op_sel:[0,1]
	s_nop 0
	v_cvt_pk_bf16_f32 v126, v126, v127
	v_cvt_pk_bf16_f32 v127, v128, v129
	v_cvt_pk_bf16_f32 v128, v122, v123
	v_cvt_pk_bf16_f32 v129, v124, v125
	v_cvt_pk_bf16_f32 v118, v118, v119
	v_cvt_pk_bf16_f32 v119, v120, v121
	v_cvt_pk_bf16_f32 v120, v114, v115
	v_cvt_pk_bf16_f32 v121, v116, v117
	v_cvt_pk_bf16_f32 v110, v110, v111
	v_cvt_pk_bf16_f32 v111, v112, v113
	v_cvt_pk_bf16_f32 v112, v106, v107
	v_cvt_pk_bf16_f32 v113, v108, v109
	v_cvt_pk_bf16_f32 v102, v102, v103
	v_cvt_pk_bf16_f32 v103, v104, v105
	v_cvt_pk_bf16_f32 v104, v98, v99
	v_cvt_pk_bf16_f32 v105, v100, v101
	v_cvt_pk_bf16_f32 v94, v94, v95
	v_cvt_pk_bf16_f32 v95, v96, v97
	v_cvt_pk_bf16_f32 v96, v90, v91
	v_cvt_pk_bf16_f32 v97, v92, v93
	v_cvt_pk_bf16_f32 v86, v86, v87
	v_cvt_pk_bf16_f32 v87, v88, v89
	v_cvt_pk_bf16_f32 v88, v82, v83
	v_cvt_pk_bf16_f32 v89, v84, v85
	v_cvt_pk_bf16_f32 v78, v78, v79
	v_cvt_pk_bf16_f32 v79, v80, v81
	v_cvt_pk_bf16_f32 v80, v74, v75
	v_cvt_pk_bf16_f32 v81, v76, v77
	v_cvt_pk_bf16_f32 v70, v70, v71
	v_cvt_pk_bf16_f32 v71, v72, v73
	v_cvt_pk_bf16_f32 v72, v66, v67
	v_cvt_pk_bf16_f32 v73, v68, v69
	v_cvt_pk_bf16_f32 v62, v62, v63
	v_cvt_pk_bf16_f32 v63, v64, v65
	v_cvt_pk_bf16_f32 v64, v58, v59
	v_cvt_pk_bf16_f32 v65, v60, v61
	v_cvt_pk_bf16_f32 v54, v54, v55
	v_cvt_pk_bf16_f32 v55, v56, v57
	v_cvt_pk_bf16_f32 v56, v50, v51
	v_cvt_pk_bf16_f32 v57, v52, v53
	v_cvt_pk_bf16_f32 v46, v46, v47
	v_cvt_pk_bf16_f32 v47, v48, v49
	v_cvt_pk_bf16_f32 v48, v42, v43
	v_cvt_pk_bf16_f32 v49, v44, v45
	v_cvt_pk_bf16_f32 v38, v38, v39
	v_cvt_pk_bf16_f32 v39, v40, v41
	v_cvt_pk_bf16_f32 v40, v34, v35
	v_cvt_pk_bf16_f32 v41, v36, v37
	v_cvt_pk_bf16_f32 v30, v30, v31
	v_cvt_pk_bf16_f32 v31, v32, v33
	v_cvt_pk_bf16_f32 v32, v26, v27
	v_cvt_pk_bf16_f32 v33, v28, v29
	v_cvt_pk_bf16_f32 v22, v22, v23
	v_cvt_pk_bf16_f32 v23, v24, v25
	v_cvt_pk_bf16_f32 v24, v18, v19
	v_cvt_pk_bf16_f32 v25, v20, v21
	v_cvt_pk_bf16_f32 v14, v14, v15
	v_cvt_pk_bf16_f32 v15, v16, v17
	v_cvt_pk_bf16_f32 v16, v10, v11
	v_cvt_pk_bf16_f32 v17, v12, v13
	v_cvt_pk_bf16_f32 v6, v6, v7
	v_cvt_pk_bf16_f32 v7, v8, v9
	v_cvt_pk_bf16_f32 v8, v2, v3
	v_cvt_pk_bf16_f32 v9, v4, v5
	s_nop 1
	v_permlane16_swap_b32_e32 v126, v128
	v_permlane16_swap_b32_e32 v127, v129
	v_permlane16_swap_b32_e32 v118, v120
	v_permlane16_swap_b32_e32 v119, v121
	v_permlane16_swap_b32_e32 v110, v112
	v_permlane16_swap_b32_e32 v111, v113
	v_permlane16_swap_b32_e32 v102, v104
	v_permlane16_swap_b32_e32 v103, v105
	v_permlane16_swap_b32_e32 v94, v96
	v_permlane16_swap_b32_e32 v95, v97
	v_permlane16_swap_b32_e32 v86, v88
	v_permlane16_swap_b32_e32 v87, v89
	v_permlane16_swap_b32_e32 v78, v80
	v_permlane16_swap_b32_e32 v79, v81
	v_permlane16_swap_b32_e32 v70, v72
	v_permlane16_swap_b32_e32 v71, v73
	v_permlane16_swap_b32_e32 v62, v64
	v_permlane16_swap_b32_e32 v63, v65
	v_permlane16_swap_b32_e32 v54, v56
	v_permlane16_swap_b32_e32 v55, v57
	v_permlane16_swap_b32_e32 v46, v48
	v_permlane16_swap_b32_e32 v47, v49
	v_permlane16_swap_b32_e32 v38, v40
	v_permlane16_swap_b32_e32 v39, v41
	v_permlane16_swap_b32_e32 v30, v32
	v_permlane16_swap_b32_e32 v31, v33
	v_permlane16_swap_b32_e32 v22, v24
	v_permlane16_swap_b32_e32 v23, v25
	v_permlane16_swap_b32_e32 v14, v16
	v_permlane16_swap_b32_e32 v15, v17
	v_permlane16_swap_b32_e32 v6, v8
	v_permlane16_swap_b32_e32 v7, v9
	global_store_dwordx4 v[142:143], v[126:129], off
	global_store_dwordx4 v[160:161], v[118:121], off
	global_store_dwordx4 v[162:163], v[110:113], off
	global_store_dwordx4 v[164:165], v[102:105], off
	global_store_dwordx4 v[142:143], v[94:97], off offset:256
	global_store_dwordx4 v[160:161], v[86:89], off offset:256
	global_store_dwordx4 v[162:163], v[78:81], off offset:256
	global_store_dwordx4 v[164:165], v[70:73], off offset:256
	global_store_dwordx4 v[166:167], v[62:65], off
	global_store_dwordx4 v[168:169], v[54:57], off
	global_store_dwordx4 v[170:171], v[46:49], off
	global_store_dwordx4 v[172:173], v[38:41], off
	global_store_dwordx4 v[166:167], v[30:33], off offset:256
	global_store_dwordx4 v[168:169], v[22:25], off offset:256
	global_store_dwordx4 v[170:171], v[14:17], off offset:256
	global_store_dwordx4 v[172:173], v[6:9], off offset:256
	s_waitcnt vmcnt(0)
	s_cbranch_vccz .LBB0_691

; __device__ __forceinline__ unsigned pk2(float lo, float hi) { const f2_t v = {lo, hi}; return __builtin_bit_cast(unsigned, __builtin_convertvector(v, bf2_t)); }
; #define EPI_LOOP for (int ai = 0; ai < 2; ++ai) for (int bj = 0; bj < 2; ++bj) for (int m = 0; m < 4; ++m) for (int n = 0; n < 2; ++n)
; template <bool OVL, bool PANEL = false, class Epi>
; __device__ __forceinline__ void gemm_phase(const bf16_t* __restrict__ A, long lda, const bf16_t* __restrict__ Bt, long ldb, int nM, int nN, int K,
;                                            const Epi& epi, bf16_t* shm, int w0) {
;     ...
;     asm volatile("s_nop 15\n\ts_nop 15" ::: "memory");
;   __device__ __forceinline__ void operator()(const f32x4 (&acc)[2][2][4][2], int pm, int pn, int wr_, int wc_, int fr_, int fq_, bf16_t* shm, int tid) const {
;     const int wr = tid >> 8, wc = (tid >> 6) & 3, fr = tid & 15, fq = (tid >> 4) & 3;
; #pragma unroll
;     EPI_LOOP { EPI_RC
;       const float s = rstd[2 * row + 1];
;       int b, key; if (row < NLAT) { b = row >> 11; key = row & 2047; } else { b = (row - NLAT) >> 8; key = 2048 + ((row - NLAT) & 255); }
;       const int h = col >> 6, d = col & 63;
;       u32x2 w; w.x = pk2(v[0] * s, v[1] * s); w.y = pk2(v[2] * s, v[3] * s);
;       *(u32x2*)(Kn + (((long)(b * 8 + h) * 2304 + key) << 6) + d) = w; }
.LBB0_693:
	v_readlane_b32 s10, v250, 0
	s_nop 11
	v_mbcnt_lo_u32_b32 v0, -1, 0
	v_mbcnt_hi_u32_b32 v0, -1, v0
	v_readlane_b32 s16, v253, 7
	v_and_b32_e32 v146, 15, v0
	v_add_u32_e32 v139, s10, v0
	v_ashrrev_i32_e32 v130, 2, v139
	v_and_b32_e32 v130, 0xffffffc0, v130
	v_add_u32_e32 v147, s14, v130
	v_or_b32_e32 v148, v147, v146
	v_lshlrev_b32_e32 v130, 1, v148
	v_ashrrev_i32_e32 v131, 31, v130
	v_readlane_b32 s28, v253, 19
	v_readlane_b32 s29, v253, 20
	v_lshrrev_b32_e32 v0, 2, v0
	v_and_b32_e32 v0, 12, v0
	v_lshl_add_u64 v[132:133], v[130:131], 2, s[28:29]
	v_lshrrev_b32_e32 v130, 1, v139
	s_lshl_b32 s10, s13, 8
	v_and_or_b32 v0, v130, 32, v0
	v_and_or_b32 v139, v130, 64, s10
	v_lshlrev_b32_e32 v130, 1, v0
	v_add_u32_e32 v0, 0xffff0000, v147
	s_movk_i32 s15, 0xcf
	v_lshrrev_b32_e32 v145, 6, v139
	v_ashrrev_i32_e32 v139, 11, v147
	v_bitop3_b32 v140, v147, s15, v146 bitop3:0xc8
	v_lshrrev_b32_e32 v149, 8, v0
	v_cmp_gt_i32_e32 vcc, s63, v148
	s_movk_i32 s16, 0x7cf
	v_or_b32_e32 v0, 0x800, v140
	v_cndmask_b32_e32 v140, v149, v139, vcc
	v_bitop3_b32 v141, v147, s16, v146 bitop3:0xc8
	v_lshlrev_b32_e32 v150, 3, v140
	v_cndmask_b32_e32 v0, v0, v141, vcc
	v_add_u32_e32 v140, v150, v145
	s_movk_i32 s13, 0x900
	v_mad_i64_i32 v[140:141], s[10:11], v140, s13, v[0:1]
	v_readlane_b32 s18, v253, 9
	v_readlane_b32 s19, v253, 10
	v_lshlrev_b64 v[140:141], 7, v[140:141]
	v_mov_b32_e32 v131, v1
	v_lshl_add_u64 v[140:141], s[18:19], 0, v[140:141]
	v_lshl_add_u64 v[140:141], v[140:141], 0, v[130:131]
	global_load_dword v150, v[132:133], off offset:4
	global_load_dword v151, v[132:133], off offset:132
	global_load_dword v152, v[132:133], off offset:260
	global_load_dword v153, v[132:133], off offset:388
	global_load_dword v154, v[132:133], off offset:1028
	global_load_dword v155, v[132:133], off offset:1156
	global_load_dword v156, v[132:133], off offset:1284
	global_load_dword v157, v[132:133], off offset:1412
	s_mov_b32 s45, 0
	s_mov_b32 s44, 0x800
	v_lshl_add_u64 v[160:161], v[140:141], 0, s[44:45]
	s_mov_b32 s44, 0x1000
	v_lshl_add_u64 v[162:163], v[140:141], 0, s[44:45]
	s_mov_b32 s44, 0x1800
	v_lshl_add_u64 v[164:165], v[140:141], 0, s[44:45]
	s_mov_b32 s44, 0x4000
	v_lshl_add_u64 v[166:167], v[140:141], 0, s[44:45]
	s_mov_b32 s44, 0x4800
	v_lshl_add_u64 v[168:169], v[140:141], 0, s[44:45]
	s_mov_b32 s44, 0x5000
	v_lshl_add_u64 v[170:171], v[140:141], 0, s[44:45]
	s_mov_b32 s44, 0x5800
	v_lshl_add_u64 v[172:173], v[140:141], 0, s[44:45]
	s_mov_b32 s44, 0x90000
	v_lshl_add_u64 v[174:175], v[140:141], 0, s[44:45]
	v_lshl_add_u64 v[176:177], v[160:161], 0, s[44:45]
	v_lshl_add_u64 v[178:179], v[162:163], 0, s[44:45]
	v_lshl_add_u64 v[180:181], v[164:165], 0, s[44:45]
	v_lshl_add_u64 v[182:183], v[166:167], 0, s[44:45]
	v_lshl_add_u64 v[184:185], v[168:169], 0, s[44:45]
	v_lshl_add_u64 v[186:187], v[170:171], 0, s[44:45]
	v_lshl_add_u64 v[188:189], v[172:173], 0, s[44:45]
	s_waitcnt vmcnt(0)
	v_and_b32_e32 v196, 8, v130
	v_mul_u32_u24_e32 v196, 3, v196
	v_mov_b32_e32 v197, v1
	v_lshl_add_u64 v[140:141], v[140:141], 0, v[196:197]
	v_lshl_add_u64 v[160:161], v[160:161], 0, v[196:197]
	v_lshl_add_u64 v[162:163], v[162:163], 0, v[196:197]
	v_lshl_add_u64 v[164:165], v[164:165], 0, v[196:197]
	v_lshl_add_u64 v[166:167], v[166:167], 0, v[196:197]
	v_lshl_add_u64 v[168:169], v[168:169], 0, v[196:197]
	v_lshl_add_u64 v[170:171], v[170:171], 0, v[196:197]
	v_lshl_add_u64 v[172:173], v[172:173], 0, v[196:197]
	v_lshl_add_u64 v[174:175], v[174:175], 0, v[196:197]
	v_lshl_add_u64 v[176:177], v[176:177], 0, v[196:197]
	v_lshl_add_u64 v[178:179], v[178:179], 0, v[196:197]
	v_lshl_add_u64 v[180:181], v[180:181], 0, v[196:197]
	v_lshl_add_u64 v[182:183], v[182:183], 0, v[196:197]
	v_lshl_add_u64 v[184:185], v[184:185], 0, v[196:197]
	v_lshl_add_u64 v[186:187], v[186:187], 0, v[196:197]
	v_lshl_add_u64 v[188:189], v[188:189], 0, v[196:197]
	v_pk_mul_f32 v[126:127], v[126:127], v[150:151] op_sel_hi:[1,0]
	v_pk_mul_f32 v[128:129], v[128:129], v[150:151] op_sel_hi:[1,0]
	v_pk_mul_f32 v[122:123], v[122:123], v[150:151] op_sel_hi:[1,0]
	v_pk_mul_f32 v[124:125], v[124:125], v[150:151] op_sel_hi:[1,0]
	v_pk_mul_f32 v[118:119], v[118:119], v[150:151] op_sel:[0,1]
	v_pk_mul_f32 v[120:121], v[120:121], v[150:151] op_sel:[0,1]
	v_pk_mul_f32 v[114:115], v[114:115], v[150:151] op_sel:[0,1]
	v_pk_mul_f32 v[116:117], v[116:117], v[150:151] op_sel:[0,1]
	v_pk_mul_f32 v[110:111], v[110:111], v[152:153] op_sel_hi:[1,0]
	v_pk_mul_f32 v[112:113], v[112:113], v[152:153] op_sel_hi:[1,0]
	v_pk_mul_f32 v[106:107], v[106:107], v[152:153] op_sel_hi:[1,0]
	v_pk_mul_f32 v[108:109], v[108:109], v[152:153] op_sel_hi:[1,0]
	v_pk_mul_f32 v[102:103], v[102:103], v[152:153] op_sel:[0,1]
	v_pk_mul_f32 v[104:105], v[104:105], v[152:153] op_sel:[0,1]
	v_pk_mul_f32 v[98:99], v[98:99], v[152:153] op_sel:[0,1]
	v_pk_mul_f32 v[100:101], v[100:101], v[152:153] op_sel:[0,1]
	v_pk_mul_f32 v[94:95], v[94:95], v[150:151] op_sel_hi:[1,0]
	v_pk_mul_f32 v[96:97], v[96:97], v[150:151] op_sel_hi:[1,0]
	v_pk_mul_f32 v[90:91], v[90:91], v[150:151] op_sel_hi:[1,0]
	v_pk_mul_f32 v[92:93], v[92:93], v[150:151] op_sel_hi:[1,0]
	v_pk_mul_f32 v[86:87], v[86:87], v[150:151] op_sel:[0,1]
	v_pk_mul_f32 v[88:89], v[88:89], v[150:151] op_sel:[0,1]
	v_pk_mul_f32 v[82:83], v[82:83], v[150:151] op_sel:[0,1]
	v_pk_mul_f32 v[84:85], v[84:85], v[150:151] op_sel:[0,1]
	v_pk_mul_f32 v[78:79], v[78:79], v[152:153] op_sel_hi:[1,0]
	v_pk_mul_f32 v[80:81], v[80:81], v[152:153] op_sel_hi:[1,0]
	v_pk_mul_f32 v[74:75], v[74:75], v[152:153] op_sel_hi:[1,0]
	v_pk_mul_f32 v[76:77], v[76:77], v[152:153] op_sel_hi:[1,0]
	v_pk_mul_f32 v[70:71], v[70:71], v[152:153] op_sel:[0,1]
; __device__ __forceinline__ unsigned pk2(float lo, float hi) { const f2_t v = {lo, hi}; return __builtin_bit_cast(unsigned, __builtin_convertvector(v, bf2_t)); }
; #define EPI_LOOP for (int ai = 0; ai < 2; ++ai) for (int bj = 0; bj < 2; ++bj) for (int m = 0; m < 4; ++m) for (int n = 0; n < 2; ++n)
;   __device__ __forceinline__ void operator()(const f32x4 (&acc)[2][2][4][2], int pm, int pn, int wr_, int wc_, int fr_, int fq_, bf16_t* shm, int tid) const {
;     ...
;     EPI_LOOP { EPI_RC
;       const float s = rstd[2 * row + 1];
;       int b, key; if (row < NLAT) { b = row >> 11; key = row & 2047; } else { b = (row - NLAT) >> 8; key = 2048 + ((row - NLAT) & 255); }
;       const int h = col >> 6, d = col & 63;
;       u32x2 w; w.x = pk2(v[0] * s, v[1] * s); w.y = pk2(v[2] * s, v[3] * s);
;       *(u32x2*)(Kn + (((long)(b * 8 + h) * 2304 + key) << 6) + d) = w; }
	v_pk_mul_f32 v[72:73], v[72:73], v[152:153] op_sel:[0,1]
	v_pk_mul_f32 v[66:67], v[66:67], v[152:153] op_sel:[0,1]
	v_pk_mul_f32 v[68:69], v[68:69], v[152:153] op_sel:[0,1]
	v_pk_mul_f32 v[62:63], v[62:63], v[154:155] op_sel_hi:[1,0]
	v_pk_mul_f32 v[64:65], v[64:65], v[154:155] op_sel_hi:[1,0]
	v_pk_mul_f32 v[58:59], v[58:59], v[154:155] op_sel_hi:[1,0]
	v_pk_mul_f32 v[60:61], v[60:61], v[154:155] op_sel_hi:[1,0]
	v_pk_mul_f32 v[54:55], v[54:55], v[154:155] op_sel:[0,1]
	v_pk_mul_f32 v[56:57], v[56:57], v[154:155] op_sel:[0,1]
	v_pk_mul_f32 v[50:51], v[50:51], v[154:155] op_sel:[0,1]
	v_pk_mul_f32 v[52:53], v[52:53], v[154:155] op_sel:[0,1]
	v_pk_mul_f32 v[46:47], v[46:47], v[156:157] op_sel_hi:[1,0]
	v_pk_mul_f32 v[48:49], v[48:49], v[156:157] op_sel_hi:[1,0]
	v_pk_mul_f32 v[42:43], v[42:43], v[156:157] op_sel_hi:[1,0]
	v_pk_mul_f32 v[44:45], v[44:45], v[156:157] op_sel_hi:[1,0]
	v_pk_mul_f32 v[38:39], v[38:39], v[156:157] op_sel:[0,1]
	v_pk_mul_f32 v[40:41], v[40:41], v[156:157] op_sel:[0,1]
	v_pk_mul_f32 v[34:35], v[34:35], v[156:157] op_sel:[0,1]
	v_pk_mul_f32 v[36:37], v[36:37], v[156:157] op_sel:[0,1]
	v_pk_mul_f32 v[30:31], v[30:31], v[154:155] op_sel_hi:[1,0]
	v_pk_mul_f32 v[32:33], v[32:33], v[154:155] op_sel_hi:[1,0]
	v_pk_mul_f32 v[26:27], v[26:27], v[154:155] op_sel_hi:[1,0]
	v_pk_mul_f32 v[28:29], v[28:29], v[154:155] op_sel_hi:[1,0]
	v_pk_mul_f32 v[22:23], v[22:23], v[154:155] op_sel:[0,1]
	v_pk_mul_f32 v[24:25], v[24:25], v[154:155] op_sel:[0,1]
	v_pk_mul_f32 v[18:19], v[18:19], v[154:155] op_sel:[0,1]
	v_pk_mul_f32 v[20:21], v[20:21], v[154:155] op_sel:[0,1]
	v_pk_mul_f32 v[14:15], v[14:15], v[156:157] op_sel_hi:[1,0]
	v_pk_mul_f32 v[16:17], v[16:17], v[156:157] op_sel_hi:[1,0]
	v_pk_mul_f32 v[10:11], v[10:11], v[156:157] op_sel_hi:[1,0]
	v_pk_mul_f32 v[12:13], v[12:13], v[156:157] op_sel_hi:[1,0]
	v_pk_mul_f32 v[6:7], v[6:7], v[156:157] op_sel:[0,1]
	v_pk_mul_f32 v[8:9], v[8:9], v[156:157] op_sel:[0,1]
	v_pk_mul_f32 v[2:3], v[2:3], v[156:157] op_sel:[0,1]
	v_pk_mul_f32 v[4:5], v[4:5], v[156:157] op_sel:[0,1]
	s_nop 0
	v_cvt_pk_bf16_f32 v126, v126, v127
	v_cvt_pk_bf16_f32 v127, v128, v129
	v_cvt_pk_bf16_f32 v128, v122, v123
	v_cvt_pk_bf16_f32 v129, v124, v125
	v_cvt_pk_bf16_f32 v118, v118, v119
	v_cvt_pk_bf16_f32 v119, v120, v121
	v_cvt_pk_bf16_f32 v120, v114, v115
	v_cvt_pk_bf16_f32 v121, v116, v117
	v_cvt_pk_bf16_f32 v110, v110, v111
	v_cvt_pk_bf16_f32 v111, v112, v113
	v_cvt_pk_bf16_f32 v112, v106, v107
	v_cvt_pk_bf16_f32 v113, v108, v109
	v_cvt_pk_bf16_f32 v102, v102, v103
	v_cvt_pk_bf16_f32 v103, v104, v105
	v_cvt_pk_bf16_f32 v104, v98, v99
	v_cvt_pk_bf16_f32 v105, v100, v101
	v_cvt_pk_bf16_f32 v94, v94, v95
	v_cvt_pk_bf16_f32 v95, v96, v97
	v_cvt_pk_bf16_f32 v96, v90, v91
	v_cvt_pk_bf16_f32 v97, v92, v93
	v_cvt_pk_bf16_f32 v86, v86, v87
	v_cvt_pk_bf16_f32 v87, v88, v89
	v_cvt_pk_bf16_f32 v88, v82, v83
	v_cvt_pk_bf16_f32 v89, v84, v85
	v_cvt_pk_bf16_f32 v78, v78, v79
	v_cvt_pk_bf16_f32 v79, v80, v81
	v_cvt_pk_bf16_f32 v80, v74, v75
	v_cvt_pk_bf16_f32 v81, v76, v77
	v_cvt_pk_bf16_f32 v70, v70, v71
	v_cvt_pk_bf16_f32 v71, v72, v73
	v_cvt_pk_bf16_f32 v72, v66, v67
	v_cvt_pk_bf16_f32 v73, v68, v69
	v_cvt_pk_bf16_f32 v62, v62, v63
	v_cvt_pk_bf16_f32 v63, v64, v65
	v_cvt_pk_bf16_f32 v64, v58, v59
	v_cvt_pk_bf16_f32 v65, v60, v61
	v_cvt_pk_bf16_f32 v54, v54, v55
	v_cvt_pk_bf16_f32 v55, v56, v57
	v_cvt_pk_bf16_f32 v56, v50, v51
	v_cvt_pk_bf16_f32 v57, v52, v53
	v_cvt_pk_bf16_f32 v46, v46, v47
	v_cvt_pk_bf16_f32 v47, v48, v49
	v_cvt_pk_bf16_f32 v48, v42, v43
	v_cvt_pk_bf16_f32 v49, v44, v45
	v_cvt_pk_bf16_f32 v38, v38, v39
	v_cvt_pk_bf16_f32 v39, v40, v41
	v_cvt_pk_bf16_f32 v40, v34, v35
	v_cvt_pk_bf16_f32 v41, v36, v37
	v_cvt_pk_bf16_f32 v30, v30, v31
	v_cvt_pk_bf16_f32 v31, v32, v33
	v_cvt_pk_bf16_f32 v32, v26, v27
	v_cvt_pk_bf16_f32 v33, v28, v29
	v_cvt_pk_bf16_f32 v22, v22, v23
	v_cvt_pk_bf16_f32 v23, v24, v25
	v_cvt_pk_bf16_f32 v24, v18, v19
	v_cvt_pk_bf16_f32 v25, v20, v21
	v_cvt_pk_bf16_f32 v14, v14, v15
	v_cvt_pk_bf16_f32 v15, v16, v17
	v_cvt_pk_bf16_f32 v16, v10, v11
	v_cvt_pk_bf16_f32 v17, v12, v13
	v_cvt_pk_bf16_f32 v6, v6, v7
	v_cvt_pk_bf16_f32 v7, v8, v9
	v_cvt_pk_bf16_f32 v8, v2, v3
	v_cvt_pk_bf16_f32 v9, v4, v5
	s_nop 1
	v_permlane16_swap_b32_e32 v126, v128
	v_permlane16_swap_b32_e32 v127, v129
	v_permlane16_swap_b32_e32 v118, v120
	v_permlane16_swap_b32_e32 v119, v121
	v_permlane16_swap_b32_e32 v110, v112
	v_permlane16_swap_b32_e32 v111, v113
	v_permlane16_swap_b32_e32 v102, v104
	v_permlane16_swap_b32_e32 v103, v105
	v_permlane16_swap_b32_e32 v94, v96
	v_permlane16_swap_b32_e32 v95, v97
	v_permlane16_swap_b32_e32 v86, v88
	v_permlane16_swap_b32_e32 v87, v89
	v_permlane16_swap_b32_e32 v78, v80
	v_permlane16_swap_b32_e32 v79, v81
	v_permlane16_swap_b32_e32 v70, v72
	v_permlane16_swap_b32_e32 v71, v73
	v_permlane16_swap_b32_e32 v62, v64
	v_permlane16_swap_b32_e32 v63, v65
	v_permlane16_swap_b32_e32 v54, v56
	v_permlane16_swap_b32_e32 v55, v57
	v_permlane16_swap_b32_e32 v46, v48
	v_permlane16_swap_b32_e32 v47, v49
	v_permlane16_swap_b32_e32 v38, v40
	v_permlane16_swap_b32_e32 v39, v41
	v_permlane16_swap_b32_e32 v30, v32
	v_permlane16_swap_b32_e32 v31, v33
	v_permlane16_swap_b32_e32 v22, v24
	v_permlane16_swap_b32_e32 v23, v25
	v_permlane16_swap_b32_e32 v14, v16
	v_permlane16_swap_b32_e32 v15, v17
	v_permlane16_swap_b32_e32 v6, v8
	v_permlane16_swap_b32_e32 v7, v9
	global_store_dwordx4 v[140:141], v[126:129], off
	global_store_dwordx4 v[160:161], v[118:121], off
	global_store_dwordx4 v[162:163], v[110:113], off
	global_store_dwordx4 v[164:165], v[102:105], off
	global_store_dwordx4 v[174:175], v[94:97], off
	global_store_dwordx4 v[176:177], v[86:89], off
	global_store_dwordx4 v[178:179], v[78:81], off
	global_store_dwordx4 v[180:181], v[70:73], off
	global_store_dwordx4 v[166:167], v[62:65], off
	global_store_dwordx4 v[168:169], v[54:57], off
	global_store_dwordx4 v[170:171], v[46:49], off
	global_store_dwordx4 v[172:173], v[38:41], off
	global_store_dwordx4 v[182:183], v[30:33], off
	global_store_dwordx4 v[184:185], v[22:25], off
	global_store_dwordx4 v[186:187], v[14:17], off
	global_store_dwordx4 v[188:189], v[6:9], off
	s_mov_b32 s13, s12
	s_andn2_b64 vcc, exec, s[8:9]
	s_waitcnt vmcnt(0)
	s_cbranch_vccz .LBB0_702

; __device__ __forceinline__ unsigned pk2(float lo, float hi) { const f2_t v = {lo, hi}; return __builtin_bit_cast(unsigned, __builtin_convertvector(v, bf2_t)); }
; #define otid() otid_impl(w0)
; template <bool OVL, bool PANEL = false, class Epi>
; __device__ __forceinline__ void gemm_phase(const bf16_t* __restrict__ A, long lda, const bf16_t* __restrict__ Bt, long ldb, int nM, int nN, int K,
;                                            const Epi& epi, bf16_t* shm, int w0) {
;     ...
;     asm volatile("s_nop 15\n\ts_nop 15" ::: "memory");
;     { const int tid2 = otid(); epi(acc, cpm, cpn, wr, wc, fr, fq, shm, tid2); }
;   __device__ __forceinline__ void operator()(const f32x4 (&acc)[2][2][4][2], int pm, int pn, int wr, int wc, int fr, int fq, bf16_t* shm, int tid) const {
;     ...
;     for (int bj = 0; bj < 2; ++bj)
; #pragma unroll
;       for (int n = 0; n < 2; ++n) {
;         asm volatile("" ::: "memory");
;         const int col = pn * 256 + bj * 128 + wc * 32 + n * 16 + fq * 4;
;         int b, key; if (col < NLAT) { b = col >> 11; key = col & 2047; } else { b = (col - NLAT) >> 8; key = 2048 + ((col - NLAT) & 255); }
;         const float s0 = rstd[2 * col + 1], s1 = rstd[2 * col + 3], s2 = rstd[2 * col + 5], s3 = rstd[2 * col + 7];
;         bf16_t* base = Vt + ((long)(b * 512 + pm * 256 + wr * 64 + fr)) * 2304 + key;
; #pragma unroll
;         for (int ai = 0; ai < 2; ++ai)
; #pragma unroll
;           for (int m = 0; m < 4; ++m) {
;             const f32x4 v = acc[ai][bj][m][n];
;             u32x2 w; w.x = pk2(v[0] * s0, v[1] * s1); w.y = pk2(v[2] * s2, v[3] * s3);
;             *(u32x2*)(base + (long)(ai * 128 + m * 16) * 2304) = w;
;           }
.LBB0_825:
	s_add_i32 s10, s14, 0xffff0000
	s_lshl_b32 s15, s15, 8
	s_lshr_b32 s17, s10, 8
	s_lshr_b32 s18, s13, 3
	s_cmpk_lt_u32 s13, 0x100
	s_nop 11
	v_mbcnt_lo_u32_b32 v0, -1, 0
	v_mbcnt_hi_u32_b32 v0, -1, v0
	s_cselect_b64 vcc, -1, 0
	v_mov_b32_e32 v0, 0x76c
	s_and_b64 s[10:11], vcc, exec
	v_or_b32_e32 v154, s14, v150
	v_bitop3_b32 v0, s14, v0, v150 bitop3:0xc8
	s_cselect_b32 s10, s18, s17
	v_readlane_b32 s16, v253, 7
	v_cndmask_b32_e32 v136, v152, v0, vcc
	v_lshlrev_b32_e32 v0, 1, v154
	v_readlane_b32 s28, v253, 19
	v_readlane_b32 s29, v253, 20
	s_lshl_b32 s10, s10, 9
	v_readlane_b32 s20, v253, 11
	v_lshl_add_u64 v[130:131], v[0:1], 2, s[28:29]
	global_load_dword v134, v[130:131], off offset:4
	global_load_dword v135, v[130:131], off offset:12
	global_load_dword v132, v[130:131], off offset:20
	global_load_dword v133, v[130:131], off offset:28
	global_load_dword v176, v[130:131], off offset:132
	global_load_dword v177, v[130:131], off offset:140
	global_load_dword v178, v[130:131], off offset:148
	global_load_dword v179, v[130:131], off offset:156
	global_load_dword v180, v[130:131], off offset:1028
	global_load_dword v181, v[130:131], off offset:1036
	global_load_dword v182, v[130:131], off offset:1044
	global_load_dword v183, v[130:131], off offset:1052
	global_load_dword v184, v[130:131], off offset:1156
	global_load_dword v185, v[130:131], off offset:1164
	global_load_dword v186, v[130:131], off offset:1172
	global_load_dword v187, v[130:131], off offset:1180
	v_readlane_b32 s21, v253, 12
	s_add_i32 s10, s10, s15
	v_add_u32_e32 v0, s10, v151
	v_mov_b64_e32 v[130:131], s[20:21]
	v_mad_i64_i32 v[130:131], s[10:11], v0, s57, v[130:131]
	v_lshlrev_b32_e32 v0, 1, v136
	v_lshl_add_u64 v[136:137], v[130:131], 0, v[0:1]
	s_mov_b32 s13, 0x12000
	s_mov_b32 s14, 0xb4000
	v_or_b32_e32 v0, 16, v154
	v_lshlrev_b32_e32 v0, 1, v0
	s_mov_b32 s15, s2
	v_readlane_b32 s17, v253, 8
	v_readlane_b32 s18, v253, 9
	v_readlane_b32 s19, v253, 10
	v_readlane_b32 s22, v253, 13
	v_readlane_b32 s23, v253, 14
	v_readlane_b32 s24, v253, 15
	v_readlane_b32 s25, v253, 16
	v_readlane_b32 s26, v253, 17
	v_readlane_b32 s27, v253, 18
	v_readlane_b32 s30, v253, 21
	v_readlane_b32 s31, v253, 22
	s_waitcnt vmcnt(0)
	v_pk_mul_f32 v[122:123], v[122:123], v[134:135]
	s_nop 0
	v_cvt_pk_bf16_f32 v122, v122, v123
	v_pk_mul_f32 v[124:125], v[124:125], v[132:133]
	v_pk_mul_f32 v[118:119], v[118:119], v[134:135]
	v_cvt_pk_bf16_f32 v123, v124, v125
	v_add_co_u32_e64 v124, s[10:11], s13, v136
	v_pk_mul_f32 v[120:121], v[120:121], v[132:133]
	s_nop 0
	v_addc_co_u32_e64 v125, s[10:11], 0, v137, s[10:11]
	v_cvt_pk_bf16_f32 v118, v118, v119
	v_cvt_pk_bf16_f32 v119, v120, v121
	v_add_co_u32_e64 v120, s[10:11], s58, v136
	v_pk_mul_f32 v[110:111], v[110:111], v[134:135]
	s_nop 0
	v_addc_co_u32_e64 v121, s[10:11], 0, v137, s[10:11]
	v_pk_mul_f32 v[112:113], v[112:113], v[132:133]
	v_cvt_pk_bf16_f32 v110, v110, v111
	v_cvt_pk_bf16_f32 v111, v112, v113
	v_add_co_u32_e64 v112, s[10:11], s59, v136
	v_pk_mul_f32 v[106:107], v[106:107], v[134:135]
	s_nop 0
	v_addc_co_u32_e64 v113, s[10:11], 0, v137, s[10:11]
	global_store_dwordx2 v[112:113], v[110:111], off
	v_pk_mul_f32 v[110:111], v[114:115], v[134:135]
	v_pk_mul_f32 v[112:113], v[116:117], v[132:133]
	v_cvt_pk_bf16_f32 v110, v110, v111
	v_cvt_pk_bf16_f32 v111, v112, v113
	v_add_co_u32_e64 v112, s[10:11], s60, v136
	v_pk_mul_f32 v[108:109], v[108:109], v[132:133]
	s_nop 0
	v_addc_co_u32_e64 v113, s[10:11], 0, v137, s[10:11]
	v_cvt_pk_bf16_f32 v106, v106, v107
	v_cvt_pk_bf16_f32 v107, v108, v109
	v_add_co_u32_e64 v108, s[10:11], s61, v136
	v_pk_mul_f32 v[102:103], v[102:103], v[134:135]
	s_nop 0
	v_addc_co_u32_e64 v109, s[10:11], 0, v137, s[10:11]
	v_pk_mul_f32 v[104:105], v[104:105], v[132:133]
	v_cvt_pk_bf16_f32 v102, v102, v103
	v_cvt_pk_bf16_f32 v103, v104, v105
	v_add_co_u32_e64 v104, s[10:11], s14, v136
	v_pk_mul_f32 v[98:99], v[98:99], v[134:135]
	s_nop 0
	v_addc_co_u32_e64 v105, s[10:11], 0, v137, s[10:11]
	v_pk_mul_f32 v[100:101], v[100:101], v[132:133]
	v_cvt_pk_bf16_f32 v98, v98, v99
	v_cvt_pk_bf16_f32 v99, v100, v101
	v_add_co_u32_e64 v100, s[10:11], s56, v136
	v_pk_mul_f32 v[126:127], v[126:127], v[134:135]
	s_nop 0
	v_addc_co_u32_e64 v101, s[10:11], 0, v137, s[10:11]
	v_pk_mul_f32 v[128:129], v[128:129], v[132:133]
	s_movk_i32 s10, 0x77c
	v_cvt_pk_bf16_f32 v126, v126, v127
	v_cvt_pk_bf16_f32 v127, v128, v129
	global_store_dwordx2 v[100:101], v[98:99], off
	v_bitop3_b32 v98, v154, s10, 16 bitop3:0xc8
	s_movk_i32 s10, 0x7c
	global_store_dwordx2 v[136:137], v[126:127], off
	global_store_dwordx2 v[124:125], v[122:123], off
	global_store_dwordx2 v[120:121], v[118:119], off
	global_store_dwordx2 v[112:113], v[110:111], off
	global_store_dwordx2 v[108:109], v[106:107], off
	global_store_dwordx2 v[104:105], v[102:103], off
	v_bitop3_b32 v99, v154, s10, 16 bitop3:0xc8
	v_or_b32_e32 v99, 0x800, v99
	v_lshl_add_u64 v[100:101], v[0:1], 2, s[28:29]
	v_cndmask_b32_e32 v104, v99, v98, vcc
	v_mov_b32_e32 v102, v176
	v_mov_b32_e32 v103, v177
	v_mov_b32_e32 v98, v178
	v_mov_b32_e32 v99, v179
	v_lshlrev_b32_e32 v0, 1, v104
	v_lshl_add_u64 v[100:101], v[130:131], 0, v[0:1]
	v_or_b32_e32 v0, 0x80, v154
	v_lshlrev_b32_e32 v0, 1, v0
	v_pk_mul_f32 v[90:91], v[90:91], v[102:103]
	s_nop 0
	v_cvt_pk_bf16_f32 v90, v90, v91
	v_pk_mul_f32 v[92:93], v[92:93], v[98:99]
	v_pk_mul_f32 v[86:87], v[86:87], v[102:103]
	v_cvt_pk_bf16_f32 v91, v92, v93
	v_add_co_u32_e64 v92, s[10:11], s13, v100
	v_pk_mul_f32 v[88:89], v[88:89], v[98:99]
	s_nop 0
	v_addc_co_u32_e64 v93, s[10:11], 0, v101, s[10:11]
	v_cvt_pk_bf16_f32 v86, v86, v87
	v_cvt_pk_bf16_f32 v87, v88, v89
; __device__ __forceinline__ unsigned pk2(float lo, float hi) { const f2_t v = {lo, hi}; return __builtin_bit_cast(unsigned, __builtin_convertvector(v, bf2_t)); }
;   __device__ __forceinline__ void operator()(const f32x4 (&acc)[2][2][4][2], int pm, int pn, int wr, int wc, int fr, int fq, bf16_t* shm, int tid) const {
;     ...
;         for (int ai = 0; ai < 2; ++ai)
; #pragma unroll
;           for (int m = 0; m < 4; ++m) {
;             const f32x4 v = acc[ai][bj][m][n];
;             u32x2 w; w.x = pk2(v[0] * s0, v[1] * s1); w.y = pk2(v[2] * s2, v[3] * s3);
;             *(u32x2*)(base + (long)(ai * 128 + m * 16) * 2304) = w;
;           }
	v_add_co_u32_e64 v88, s[10:11], s58, v100
	v_pk_mul_f32 v[78:79], v[78:79], v[102:103]
	s_nop 0
	v_addc_co_u32_e64 v89, s[10:11], 0, v101, s[10:11]
	v_pk_mul_f32 v[80:81], v[80:81], v[98:99]
	v_cvt_pk_bf16_f32 v78, v78, v79
	v_cvt_pk_bf16_f32 v79, v80, v81
	v_add_co_u32_e64 v80, s[10:11], s59, v100
	v_pk_mul_f32 v[74:75], v[74:75], v[102:103]
	s_nop 0
	v_addc_co_u32_e64 v81, s[10:11], 0, v101, s[10:11]
	global_store_dwordx2 v[80:81], v[78:79], off
	v_pk_mul_f32 v[78:79], v[82:83], v[102:103]
	v_pk_mul_f32 v[80:81], v[84:85], v[98:99]
	v_cvt_pk_bf16_f32 v78, v78, v79
	v_cvt_pk_bf16_f32 v79, v80, v81
	v_add_co_u32_e64 v80, s[10:11], s60, v100
	v_pk_mul_f32 v[76:77], v[76:77], v[98:99]
	s_nop 0
	v_addc_co_u32_e64 v81, s[10:11], 0, v101, s[10:11]
	v_cvt_pk_bf16_f32 v74, v74, v75
	v_cvt_pk_bf16_f32 v75, v76, v77
	v_add_co_u32_e64 v76, s[10:11], s61, v100
	v_pk_mul_f32 v[70:71], v[70:71], v[102:103]
	s_nop 0
	v_addc_co_u32_e64 v77, s[10:11], 0, v101, s[10:11]
	v_pk_mul_f32 v[72:73], v[72:73], v[98:99]
	v_cvt_pk_bf16_f32 v70, v70, v71
	v_cvt_pk_bf16_f32 v71, v72, v73
	v_add_co_u32_e64 v72, s[10:11], s14, v100
	v_pk_mul_f32 v[66:67], v[66:67], v[102:103]
	s_nop 0
	v_addc_co_u32_e64 v73, s[10:11], 0, v101, s[10:11]
	v_pk_mul_f32 v[68:69], v[68:69], v[98:99]
	v_cvt_pk_bf16_f32 v66, v66, v67
	v_cvt_pk_bf16_f32 v67, v68, v69
	v_add_co_u32_e64 v68, s[10:11], s56, v100
	v_pk_mul_f32 v[94:95], v[94:95], v[102:103]
	s_nop 0
	v_addc_co_u32_e64 v69, s[10:11], 0, v101, s[10:11]
	global_store_dwordx2 v[68:69], v[66:67], off
	s_movk_i32 s10, 0x7ec
	v_mov_b32_e32 v67, 0x80
	v_pk_mul_f32 v[96:97], v[96:97], v[98:99]
	v_bitop3_b32 v66, v154, s10, v67 bitop3:0xc8
	s_movk_i32 s10, 0xec
	v_cvt_pk_bf16_f32 v94, v94, v95
	v_cvt_pk_bf16_f32 v95, v96, v97
	v_bitop3_b32 v67, v154, s10, v67 bitop3:0xc8
	global_store_dwordx2 v[100:101], v[94:95], off
	global_store_dwordx2 v[92:93], v[90:91], off
	global_store_dwordx2 v[88:89], v[86:87], off
	global_store_dwordx2 v[80:81], v[78:79], off
	global_store_dwordx2 v[76:77], v[74:75], off
	global_store_dwordx2 v[72:73], v[70:71], off
	v_or_b32_e32 v67, 0x800, v67
	v_cndmask_b32_e32 v72, v67, v66, vcc
	v_lshl_add_u64 v[66:67], v[0:1], 2, s[28:29]
	v_mov_b32_e32 v70, v180
	v_mov_b32_e32 v71, v181
	v_mov_b32_e32 v68, v182
	v_mov_b32_e32 v69, v183
	v_lshlrev_b32_e32 v0, 1, v72
	v_lshl_add_u64 v[66:67], v[130:131], 0, v[0:1]
	v_or_b32_e32 v0, 0x90, v154
	v_lshlrev_b32_e32 v0, 1, v0
	v_pk_mul_f32 v[58:59], v[58:59], v[70:71]
	s_nop 0
	v_cvt_pk_bf16_f32 v58, v58, v59
	v_pk_mul_f32 v[60:61], v[60:61], v[68:69]
	v_pk_mul_f32 v[54:55], v[54:55], v[70:71]
	v_cvt_pk_bf16_f32 v59, v60, v61
	v_add_co_u32_e64 v60, s[10:11], s13, v66
	v_pk_mul_f32 v[56:57], v[56:57], v[68:69]
	s_nop 0
	v_addc_co_u32_e64 v61, s[10:11], 0, v67, s[10:11]
	v_cvt_pk_bf16_f32 v54, v54, v55
	v_cvt_pk_bf16_f32 v55, v56, v57
	v_add_co_u32_e64 v56, s[10:11], s58, v66
	v_pk_mul_f32 v[46:47], v[46:47], v[70:71]
	s_nop 0
	v_addc_co_u32_e64 v57, s[10:11], 0, v67, s[10:11]
	v_pk_mul_f32 v[48:49], v[48:49], v[68:69]
	v_cvt_pk_bf16_f32 v46, v46, v47
	v_cvt_pk_bf16_f32 v47, v48, v49
	v_add_co_u32_e64 v48, s[10:11], s59, v66
	v_pk_mul_f32 v[42:43], v[42:43], v[70:71]
	s_nop 0
	v_addc_co_u32_e64 v49, s[10:11], 0, v67, s[10:11]
	global_store_dwordx2 v[48:49], v[46:47], off
	v_pk_mul_f32 v[46:47], v[50:51], v[70:71]
	v_pk_mul_f32 v[48:49], v[52:53], v[68:69]
	v_cvt_pk_bf16_f32 v46, v46, v47
	v_cvt_pk_bf16_f32 v47, v48, v49
	v_add_co_u32_e64 v48, s[10:11], s60, v66
	v_pk_mul_f32 v[44:45], v[44:45], v[68:69]
	s_nop 0
	v_addc_co_u32_e64 v49, s[10:11], 0, v67, s[10:11]
	v_cvt_pk_bf16_f32 v42, v42, v43
	v_cvt_pk_bf16_f32 v43, v44, v45
	v_add_co_u32_e64 v44, s[10:11], s61, v66
	v_pk_mul_f32 v[38:39], v[38:39], v[70:71]
; __device__ __forceinline__ unsigned pk2(float lo, float hi) { const f2_t v = {lo, hi}; return __builtin_bit_cast(unsigned, __builtin_convertvector(v, bf2_t)); }
; #define WAIT_V(n) asm volatile("s_waitcnt vmcnt(" #n ")" ::: "memory")
; template <bool OVL, bool PANEL = false, class Epi>
; __device__ __forceinline__ void gemm_phase(const bf16_t* __restrict__ A, long lda, const bf16_t* __restrict__ Bt, long ldb, int nM, int nN, int K,
;                                            const Epi& epi, bf16_t* shm, int w0) {
;     ...
;     if (OVL) WAIT_V(0);
;   __device__ __forceinline__ void operator()(const f32x4 (&acc)[2][2][4][2], int pm, int pn, int wr, int wc, int fr, int fq, bf16_t* shm, int tid) const {
;     ...
;         for (int ai = 0; ai < 2; ++ai)
; #pragma unroll
;           for (int m = 0; m < 4; ++m) {
;             const f32x4 v = acc[ai][bj][m][n];
;             u32x2 w; w.x = pk2(v[0] * s0, v[1] * s1); w.y = pk2(v[2] * s2, v[3] * s3);
;             *(u32x2*)(base + (long)(ai * 128 + m * 16) * 2304) = w;
;           }
	s_nop 0
	v_addc_co_u32_e64 v45, s[10:11], 0, v67, s[10:11]
	v_pk_mul_f32 v[40:41], v[40:41], v[68:69]
	v_cvt_pk_bf16_f32 v38, v38, v39
	v_cvt_pk_bf16_f32 v39, v40, v41
	v_add_co_u32_e64 v40, s[10:11], s14, v66
	v_pk_mul_f32 v[34:35], v[34:35], v[70:71]
	s_nop 0
	v_addc_co_u32_e64 v41, s[10:11], 0, v67, s[10:11]
	v_pk_mul_f32 v[36:37], v[36:37], v[68:69]
	v_cvt_pk_bf16_f32 v34, v34, v35
	v_cvt_pk_bf16_f32 v35, v36, v37
	v_add_co_u32_e64 v36, s[10:11], s56, v66
	v_pk_mul_f32 v[62:63], v[62:63], v[70:71]
	s_nop 0
	v_addc_co_u32_e64 v37, s[10:11], 0, v67, s[10:11]
	global_store_dwordx2 v[36:37], v[34:35], off
	s_movk_i32 s10, 0x7fc
	v_mov_b32_e32 v35, 0x90
	v_pk_mul_f32 v[64:65], v[64:65], v[68:69]
	v_bitop3_b32 v34, v154, s10, v35 bitop3:0xc8
	s_movk_i32 s10, 0xfc
	v_cvt_pk_bf16_f32 v62, v62, v63
	v_cvt_pk_bf16_f32 v63, v64, v65
	v_bitop3_b32 v35, v154, s10, v35 bitop3:0xc8
	global_store_dwordx2 v[66:67], v[62:63], off
	global_store_dwordx2 v[60:61], v[58:59], off
	global_store_dwordx2 v[56:57], v[54:55], off
	global_store_dwordx2 v[48:49], v[46:47], off
	global_store_dwordx2 v[44:45], v[42:43], off
	global_store_dwordx2 v[40:41], v[38:39], off
	v_or_b32_e32 v35, 0x800, v35
	v_cndmask_b32_e32 v40, v35, v34, vcc
	v_lshl_add_u64 v[34:35], v[0:1], 2, s[28:29]
	v_mov_b32_e32 v38, v184
	v_mov_b32_e32 v39, v185
	v_mov_b32_e32 v36, v186
	v_mov_b32_e32 v37, v187
	v_lshlrev_b32_e32 v0, 1, v40
	v_lshl_add_u64 v[34:35], v[130:131], 0, v[0:1]
	v_pk_mul_f32 v[26:27], v[26:27], v[38:39]
	s_nop 0
	v_cvt_pk_bf16_f32 v26, v26, v27
	v_pk_mul_f32 v[28:29], v[28:29], v[36:37]
	v_pk_mul_f32 v[22:23], v[22:23], v[38:39]
	v_cvt_pk_bf16_f32 v27, v28, v29
	v_add_co_u32_e32 v28, vcc, s13, v34
	v_pk_mul_f32 v[24:25], v[24:25], v[36:37]
	s_nop 0
	v_addc_co_u32_e32 v29, vcc, 0, v35, vcc
	v_cvt_pk_bf16_f32 v22, v22, v23
	v_cvt_pk_bf16_f32 v23, v24, v25
	v_add_co_u32_e32 v24, vcc, s58, v34
	v_pk_mul_f32 v[14:15], v[14:15], v[38:39]
	s_nop 0
	v_addc_co_u32_e32 v25, vcc, 0, v35, vcc
	v_pk_mul_f32 v[16:17], v[16:17], v[36:37]
	v_cvt_pk_bf16_f32 v14, v14, v15
	v_cvt_pk_bf16_f32 v15, v16, v17
	v_add_co_u32_e32 v16, vcc, s59, v34
	v_pk_mul_f32 v[10:11], v[10:11], v[38:39]
	s_nop 0
	v_addc_co_u32_e32 v17, vcc, 0, v35, vcc
	global_store_dwordx2 v[16:17], v[14:15], off
	v_pk_mul_f32 v[14:15], v[18:19], v[38:39]
	v_pk_mul_f32 v[16:17], v[20:21], v[36:37]
	v_cvt_pk_bf16_f32 v14, v14, v15
	v_cvt_pk_bf16_f32 v15, v16, v17
	v_add_co_u32_e32 v16, vcc, s60, v34
	v_pk_mul_f32 v[12:13], v[12:13], v[36:37]
	s_nop 0
	v_addc_co_u32_e32 v17, vcc, 0, v35, vcc
	v_cvt_pk_bf16_f32 v10, v10, v11
	v_cvt_pk_bf16_f32 v11, v12, v13
	v_add_co_u32_e32 v12, vcc, s61, v34
	v_pk_mul_f32 v[6:7], v[6:7], v[38:39]
	s_nop 0
	v_addc_co_u32_e32 v13, vcc, 0, v35, vcc
	v_pk_mul_f32 v[8:9], v[8:9], v[36:37]
	v_cvt_pk_bf16_f32 v6, v6, v7
	v_cvt_pk_bf16_f32 v7, v8, v9
	v_add_co_u32_e32 v8, vcc, s14, v34
	v_pk_mul_f32 v[2:3], v[2:3], v[38:39]
	s_nop 0
	v_addc_co_u32_e32 v9, vcc, 0, v35, vcc
	v_pk_mul_f32 v[4:5], v[4:5], v[36:37]
	v_pk_mul_f32 v[30:31], v[30:31], v[38:39]
	v_pk_mul_f32 v[32:33], v[32:33], v[36:37]
	v_cvt_pk_bf16_f32 v2, v2, v3
	v_cvt_pk_bf16_f32 v3, v4, v5
	v_add_co_u32_e32 v4, vcc, 0xc6000, v34
	v_cvt_pk_bf16_f32 v30, v30, v31
	v_cvt_pk_bf16_f32 v31, v32, v33
	v_addc_co_u32_e32 v5, vcc, 0, v35, vcc
	global_store_dwordx2 v[34:35], v[30:31], off
	global_store_dwordx2 v[28:29], v[26:27], off
	global_store_dwordx2 v[24:25], v[22:23], off
	global_store_dwordx2 v[16:17], v[14:15], off
	global_store_dwordx2 v[12:13], v[10:11], off
	global_store_dwordx2 v[8:9], v[6:7], off
	global_store_dwordx2 v[4:5], v[2:3], off
	s_waitcnt vmcnt(0)
	s_andn2_b64 vcc, exec, s[8:9]
	s_mov_b32 s13, s12
	s_cbranch_vccz .LBB0_834

; __device__ __forceinline__ unsigned pk2(float lo, float hi) { const f2_t v = {lo, hi}; return __builtin_bit_cast(unsigned, __builtin_convertvector(v, bf2_t)); }
; __device__ __forceinline__ long state_idx(int mx, int b, int h, int dir, int c) { return ((((long)(mx * 32 + b) * 4 + h) * 2 + dir) * 36 + c); }
; __device__ void scanA_phase(const Params& p, int l, char* shm, int w0) {
;     ...
; #pragma unroll
;     for (int q = 0; q < 2; ++q) {
;       const int id = wv * 2 + q, dir = id >> 3, dti = (id >> 2) & 1, eti = id & 3;
;       f32x4 acc = {0.f, 0.f, 0.f, 0.f};
; #pragma unroll
;       for (int ks = 0; ks < 2; ++ks) acc = mma16(KHT + (dir * 32 + dti * 16) * SSTR + ks * 32, VT + (eti * 16) * SSTR + ks * 32, acc, fr, fq);
;       asm volatile("s_nop 15\n\ts_nop 15" : "+v"(acc[0]), "+v"(acc[1]), "+v"(acc[2]), "+v"(acc[3]));
;       u32x2 wst; wst.x = pk2(acc[0], acc[1]); wst.y = pk2(acc[2], acc[3]);
;       *(u32x2*)(p.St + state_idx(mx, b, h, dir, c) * 2048 + (eti * 16 + fr) * 32 + dti * 16 + fq * 4) = wst;
;     }
.LBB0_848:
	s_or_b64 exec, exec, s[66:67]
	v_lshl_add_u64 v[62:63], v[62:63], 0, v[42:43]
	v_lshl_add_u64 v[62:63], v[62:63], 0, v[64:65]
	v_mad_u64_u32 v[60:61], s[4:5], v62, 36, v[60:61]
	v_mov_b32_e32 v62, v61
	v_mad_u64_u32 v[62:63], s[4:5], v63, 36, v[62:63]
	v_mov_b32_e32 v61, v62
	s_waitcnt lgkmcnt(0)
	s_barrier
	v_lshlrev_b64 v[72:73], 12, v[60:61]
	ds_read_b128 v[60:63], v44 offset:35840
	ds_read_b128 v[64:67], v85 offset:26624
	s_waitcnt lgkmcnt(0)
	v_mfma_f32_16x16x32_bf16 v[60:63], v[60:63], v[64:67], 0
	ds_read_b128 v[64:67], v44 offset:35904
	ds_read_b128 v[68:71], v85 offset:26688
	v_add_u32_e32 v78, s17, v78
	v_add_u32_e32 v45, s18, v45
	s_waitcnt lgkmcnt(0)
	v_mfma_f32_16x16x32_bf16 v[60:63], v[64:67], v[68:71], v[60:63]
	s_nop 11
	s_andn2_b64 vcc, exec, s[44:45]
	s_nop 6
	v_cvt_pk_bf16_f32 v60, v60, v61
	v_cvt_pk_bf16_f32 v61, v62, v63
	v_lshl_add_u64 v[62:63], v[52:53], 0, v[72:73]
	global_store_dwordx2 v[62:63], v[60:61], off
	ds_read_b128 v[60:63], v44 offset:35840
	ds_read_b128 v[64:67], v85 offset:28928
	s_waitcnt lgkmcnt(0)
	v_mfma_f32_16x16x32_bf16 v[60:63], v[60:63], v[64:67], 0
	ds_read_b128 v[64:67], v44 offset:35904
	ds_read_b128 v[68:71], v85 offset:28992
	s_waitcnt lgkmcnt(0)
	v_mfma_f32_16x16x32_bf16 v[60:63], v[64:67], v[68:71], v[60:63]
	s_nop 11
	s_nop 7
	v_cvt_pk_bf16_f32 v60, v60, v61
	v_cvt_pk_bf16_f32 v61, v62, v63
	v_lshl_add_u64 v[62:63], v[54:55], 0, v[72:73]
	global_store_dwordx2 v[62:63], v[60:61], off
	s_cbranch_vccz .LBB0_926

; __device__ __forceinline__ unsigned pk2(float lo, float hi) { const f2_t v = {lo, hi}; return __builtin_bit_cast(unsigned, __builtin_convertvector(v, bf2_t)); }
; #define otid() otid_impl(w0)
; #define EPI_LOOP for (int ai = 0; ai < 2; ++ai) for (int bj = 0; bj < 2; ++bj) for (int m = 0; m < 4; ++m) for (int n = 0; n < 2; ++n)
; template <bool OVL, bool PANEL = false, class Epi>
; __device__ __forceinline__ void gemm_phase(const bf16_t* __restrict__ A, long lda, const bf16_t* __restrict__ Bt, long ldb, int nM, int nN, int K,
;                                            const Epi& epi, bf16_t* shm, int w0) {
;     ...
;     asm volatile("s_nop 15\n\ts_nop 15" ::: "memory");
;     { const int tid2 = otid(); epi(acc, cpm, cpn, wr, wc, fr, fq, shm, tid2); }
;   __device__ __forceinline__ void operator()(const f32x4 (&acc)[2][2][4][2], int pm, int pn, int wr, int wc, int fr, int fq, bf16_t* shm, int tid) const {
; #pragma unroll
;     EPI_LOOP { EPI_RC
;       if (col < DIN) { u32x2 w; w.x = pk2(v[0], v[1]); w.y = pk2(v[2], v[3]); *(u32x2*)(P + (long)row * DIN + col) = w; } }
;   }
.LBB0_1060:
	s_nop 11
	v_mbcnt_lo_u32_b32 v0, -1, 0
	v_mbcnt_hi_u32_b32 v0, -1, v0
	v_readlane_b32 s40, v252, 20
	v_add_u32_e32 v0, s0, v146
	s_movk_i32 s0, 0xf80
	v_or_b32_e32 v130, s12, v145
	v_mad_i64_i32 v[132:133], s[0:1], v0, s0, 0
	v_readlane_b32 s48, v252, 28
	v_readlane_b32 s49, v252, 29
	v_cmp_gt_i32_e32 vcc, s59, v130
	v_ashrrev_i32_e32 v131, 31, v130
	v_lshl_add_u64 v[132:133], s[48:49], 0, v[132:133]
	v_and_b32_e32 v192, 4, v145
	v_mul_u32_u24_e32 v193, 3, v192
	v_add_u32_e32 v193, v130, v193
	v_mul_u32_u24_e32 v192, 6, v192
	v_add_u32_e32 v194, 0x80, v193
	v_cmp_gt_i32_e64 s[44:45], s59, v193
	v_cmp_gt_i32_e64 s[46:47], s59, v194
	v_lshl_add_u64 v[176:177], v[130:131], 1, v[132:133]
	v_mov_b32_e32 v193, v1
	v_mov_b32_e32 v194, v192
	v_mov_b32_e32 v195, v1
	v_lshl_add_u64 v[176:177], v[176:177], 0, v[194:195]
	s_mov_b32 s49, 0
	s_mov_b32 s48, 0xf800
	v_lshl_add_u64 v[178:179], v[176:177], 0, s[48:49]
	s_mov_b32 s48, 0x1f000
	v_lshl_add_u64 v[180:181], v[176:177], 0, s[48:49]
	s_mov_b32 s48, 0x2e800
	v_lshl_add_u64 v[182:183], v[176:177], 0, s[48:49]
	s_mov_b32 s48, 0x7c000
	v_lshl_add_u64 v[184:185], v[176:177], 0, s[48:49]
	s_mov_b32 s48, 0x8b800
	v_lshl_add_u64 v[186:187], v[176:177], 0, s[48:49]
	s_mov_b32 s48, 0x9b000
	v_lshl_add_u64 v[188:189], v[176:177], 0, s[48:49]
	s_mov_b32 s48, 0xaa800
	v_lshl_add_u64 v[190:191], v[176:177], 0, s[48:49]
	v_cvt_pk_bf16_f32 v126, v126, v127
	v_cvt_pk_bf16_f32 v127, v128, v129
	v_cvt_pk_bf16_f32 v128, v122, v123
	v_cvt_pk_bf16_f32 v129, v124, v125
	v_cvt_pk_bf16_f32 v118, v118, v119
	v_cvt_pk_bf16_f32 v119, v120, v121
	v_cvt_pk_bf16_f32 v120, v114, v115
	v_cvt_pk_bf16_f32 v121, v116, v117
	v_cvt_pk_bf16_f32 v110, v110, v111
	v_cvt_pk_bf16_f32 v111, v112, v113
	v_cvt_pk_bf16_f32 v112, v106, v107
	v_cvt_pk_bf16_f32 v113, v108, v109
	v_cvt_pk_bf16_f32 v102, v102, v103
	v_cvt_pk_bf16_f32 v103, v104, v105
	v_cvt_pk_bf16_f32 v104, v98, v99
	v_cvt_pk_bf16_f32 v105, v100, v101
	v_cvt_pk_bf16_f32 v94, v94, v95
	v_cvt_pk_bf16_f32 v95, v96, v97
	v_cvt_pk_bf16_f32 v96, v90, v91
	v_cvt_pk_bf16_f32 v97, v92, v93
	v_cvt_pk_bf16_f32 v86, v86, v87
	v_cvt_pk_bf16_f32 v87, v88, v89
	v_cvt_pk_bf16_f32 v88, v82, v83
	v_cvt_pk_bf16_f32 v89, v84, v85
	v_cvt_pk_bf16_f32 v78, v78, v79
	v_cvt_pk_bf16_f32 v79, v80, v81
	v_cvt_pk_bf16_f32 v80, v74, v75
	v_cvt_pk_bf16_f32 v81, v76, v77
	v_cvt_pk_bf16_f32 v70, v70, v71
	v_cvt_pk_bf16_f32 v71, v72, v73
	v_cvt_pk_bf16_f32 v72, v66, v67
	v_cvt_pk_bf16_f32 v73, v68, v69
	v_cvt_pk_bf16_f32 v62, v62, v63
	v_cvt_pk_bf16_f32 v63, v64, v65
	v_cvt_pk_bf16_f32 v64, v58, v59
	v_cvt_pk_bf16_f32 v65, v60, v61
	v_cvt_pk_bf16_f32 v54, v54, v55
	v_cvt_pk_bf16_f32 v55, v56, v57
	v_cvt_pk_bf16_f32 v56, v50, v51
	v_cvt_pk_bf16_f32 v57, v52, v53
	v_cvt_pk_bf16_f32 v46, v46, v47
	v_cvt_pk_bf16_f32 v47, v48, v49
	v_cvt_pk_bf16_f32 v48, v42, v43
	v_cvt_pk_bf16_f32 v49, v44, v45
	v_cvt_pk_bf16_f32 v38, v38, v39
	v_cvt_pk_bf16_f32 v39, v40, v41
	v_cvt_pk_bf16_f32 v40, v34, v35
	v_cvt_pk_bf16_f32 v41, v36, v37
	v_cvt_pk_bf16_f32 v30, v30, v31
	v_cvt_pk_bf16_f32 v31, v32, v33
	v_cvt_pk_bf16_f32 v32, v26, v27
	v_cvt_pk_bf16_f32 v33, v28, v29
	v_cvt_pk_bf16_f32 v22, v22, v23
	v_cvt_pk_bf16_f32 v23, v24, v25
	v_cvt_pk_bf16_f32 v24, v18, v19
	v_cvt_pk_bf16_f32 v25, v20, v21
	v_cvt_pk_bf16_f32 v14, v14, v15
	v_cvt_pk_bf16_f32 v15, v16, v17
	v_cvt_pk_bf16_f32 v16, v10, v11
	v_cvt_pk_bf16_f32 v17, v12, v13
	v_cvt_pk_bf16_f32 v6, v6, v7
	v_cvt_pk_bf16_f32 v7, v8, v9
	v_cvt_pk_bf16_f32 v8, v2, v3
	v_cvt_pk_bf16_f32 v9, v4, v5
	s_nop 1
	v_permlane16_swap_b32_e32 v126, v128
	v_permlane16_swap_b32_e32 v127, v129
	v_permlane16_swap_b32_e32 v118, v120
	v_permlane16_swap_b32_e32 v119, v121
	v_permlane16_swap_b32_e32 v110, v112
	v_permlane16_swap_b32_e32 v111, v113
	v_permlane16_swap_b32_e32 v102, v104
	v_permlane16_swap_b32_e32 v103, v105
	v_permlane16_swap_b32_e32 v94, v96
	v_permlane16_swap_b32_e32 v95, v97
	v_permlane16_swap_b32_e32 v86, v88
	v_permlane16_swap_b32_e32 v87, v89
	v_permlane16_swap_b32_e32 v78, v80
	v_permlane16_swap_b32_e32 v79, v81
	v_permlane16_swap_b32_e32 v70, v72
	v_permlane16_swap_b32_e32 v71, v73
	v_permlane16_swap_b32_e32 v62, v64
	v_permlane16_swap_b32_e32 v63, v65
	v_permlane16_swap_b32_e32 v54, v56
	v_permlane16_swap_b32_e32 v55, v57
	v_permlane16_swap_b32_e32 v46, v48
	v_permlane16_swap_b32_e32 v47, v49
	v_permlane16_swap_b32_e32 v38, v40
	v_permlane16_swap_b32_e32 v39, v41
	v_permlane16_swap_b32_e32 v30, v32
	v_permlane16_swap_b32_e32 v31, v33
	v_permlane16_swap_b32_e32 v22, v24
	v_permlane16_swap_b32_e32 v23, v25
	v_permlane16_swap_b32_e32 v14, v16
	v_permlane16_swap_b32_e32 v15, v17
	v_permlane16_swap_b32_e32 v6, v8
	v_permlane16_swap_b32_e32 v7, v9
	v_or_b32_e32 v192, 16, v130
	v_cmp_gt_i32_e64 s[10:11], s59, v192
	v_or_b32_e32 v192, 0x80, v130
	v_cmp_gt_i32_e64 s[12:13], s59, v192
	v_or_b32_e32 v192, 0x90, v130
	v_cmp_gt_i32_e64 s[14:15], s59, v192
	v_readlane_b32 s40, v252, 20
	v_readlane_b32 s41, v252, 21
	v_readlane_b32 s42, v252, 22
	v_readlane_b32 s43, v252, 23
	s_and_saveexec_b64 s[0:1], s[44:45]
	global_store_dwordx4 v[176:177], v[126:129], off
	global_store_dwordx4 v[178:179], v[118:121], off
	global_store_dwordx4 v[180:181], v[110:113], off
	global_store_dwordx4 v[182:183], v[102:105], off
	global_store_dwordx4 v[184:185], v[62:65], off
	global_store_dwordx4 v[186:187], v[54:57], off
	global_store_dwordx4 v[188:189], v[46:49], off
	global_store_dwordx4 v[190:191], v[38:41], off
	s_or_b64 exec, exec, s[0:1]
	s_and_saveexec_b64 s[0:1], s[46:47]
	global_store_dwordx4 v[176:177], v[94:97], off offset:256
	global_store_dwordx4 v[178:179], v[86:89], off offset:256
	global_store_dwordx4 v[180:181], v[78:81], off offset:256
	global_store_dwordx4 v[182:183], v[70:73], off offset:256
	global_store_dwordx4 v[184:185], v[30:33], off offset:256
	global_store_dwordx4 v[186:187], v[22:25], off offset:256
	global_store_dwordx4 v[188:189], v[14:17], off offset:256
	global_store_dwordx4 v[190:191], v[6:9], off offset:256
	s_branch .LBB0_1049
